# FFN-up fused epilogue: conv-weight loads for second column half hoisted into dead accumulators, counted vmcnt instead of full drains
# speedup vs baseline: 1.0033x; 1.0033x over previous
; #define PG8_STAGE(bufoff, gbase, voff) do { _Pragma("unroll") for (int _i = 0; _i < 2; ++_i) \
;         __builtin_amdgcn_global_load_lds((const unsigned*)((const char*)(gbase) + (voff)[_i]), (LAS unsigned*)(lds + (bufoff) + ldsw + _i * 8192), 16, 0, 0); } while (0)
; #define PG8_LDA(dst, b, h) do { _Pragma("unroll") for (int m = 0; m < 4; ++m) _Pragma("unroll") for (int k = 0; k < 2; ++k) dst[m][k] = *(const LAS bf16x8*)(lds + PG8_SA(b, h) + aoff + m * 2048 + k * 1024); } while (0)
; #define PG8_LDB(dst, b, h) do { _Pragma("unroll") for (int n = 0; n < 2; ++n) _Pragma("unroll") for (int k = 0; k < 2; ++k) dst[n][k] = *(const LAS bf16x8*)(lds + PG8_SB(b, h) + boff + n * 2048 + k * 1024); } while (0)
; #define PG8_WAIT_V(n) asm volatile("s_waitcnt vmcnt(" #n ")" ::: "memory")
; #define PG8_WAIT_L(n) asm volatile("s_waitcnt lgkmcnt(" #n ")" ::: "memory")
; #define PG8_BAR __builtin_amdgcn_s_barrier()
; #define PG8_SCHED __builtin_amdgcn_sched_barrier(0)
; template <class F>
; DI void gemm_phase(const int tid, LAS unsigned char* lds, const bf16_t* Ap, int lda, const bf16_t* Bp, int ldb, int M, int N, int K, int G, int c, bool direct, const F& E) {
;     ...
;         for (int t = 0; t < nt; t += 2) {
;             const bool last = (t == nt - 2);
;             const char* a1 = cA + (size_t)(t + 1) * kstep;
;             const char* a2 = last ? nA : cA + (size_t)(t + 2) * kstep; const char* b2 = last ? nB : cB + (size_t)(t + 2) * kstep;
;             const char* a3 = a2 + kstep; const char* b3 = b2 + kstep;
;             PG8_LDB(B0, 0, 0); PG8_SCHED; PG8_LDA(At, 0, 0); PG8_STAGE(PG8_SA(1, 1), a1 + hsA, voffA);
;             PG8_WAIT_L(8); PG8_BAR; PG8_WAIT_L(0); PG8_MMA(0, 0, At, B0); PG8_BAR; PG8_SCHED;
;             PG8_LDB(B1, 0, 1); PG8_STAGE(PG8_SB(0, 0), b2, voffB);
;             PG8_BAR; PG8_WAIT_L(0); PG8_MMA(0, 1, At, B1); PG8_BAR;
;             PG8_LDA(At, 0, 1); PG8_STAGE(PG8_SA(0, 0), a2, voffA);
;             PG8_BAR; PG8_WAIT_L(0); PG8_MMA(1, 0, At, B0); PG8_BAR; PG8_SCHED;
;             PG8_STAGE(PG8_SB(0, 1), b2 + hsB, voffB);
;             PG8_WAIT_V(6); PG8_BAR; PG8_MMA(1, 1, At, B1); PG8_BAR;
;             PG8_LDB(B0, 1, 0); PG8_SCHED; PG8_LDA(At, 1, 0); PG8_STAGE(PG8_SA(0, 1), a2 + hsA, voffA);
;             PG8_WAIT_L(8); PG8_BAR; PG8_WAIT_L(0); PG8_MMA(0, 0, At, B0); PG8_BAR; PG8_SCHED;
.LBB0_657:
	s_add_i32 s81, s76, 2
	s_add_u32 s78, s74, 0x80
	s_addc_u32 s77, s75, 0
	s_add_i32 s82, 0, 0x10000
	v_add_u32_e32 v140, s82, v189
	ds_read_b128 v[128:131], v140
	ds_read_b128 v[132:135], v140 offset:1024
	ds_read_b128 v[136:139], v140 offset:2048
	ds_read_b128 v[140:143], v140 offset:3072
	s_cmp_eq_u32 s67, s76
	s_cselect_b32 s76, s0, s78
	s_cselect_b32 s77, s1, s77
	s_cselect_b32 s79, s5, s80
	s_cselect_b32 s78, s4, s71
	v_lshl_add_u64 v[208:209], s[74:75], 0, v[204:205]
	s_add_i32 m0, s28, 0xc000
	ds_read_b128 v[144:147], v197
	ds_read_b128 v[148:151], v197 offset:1024
	ds_read_b128 v[152:155], v197 offset:2048
	ds_read_b128 v[156:159], v197 offset:3072
	ds_read_b128 v[160:163], v197 offset:4096
	ds_read_b128 v[164:167], v197 offset:5120
	ds_read_b128 v[168:171], v197 offset:6144
	ds_read_b128 v[172:175], v197 offset:7168
	global_load_lds_dwordx4 v[208:209], off
	v_lshl_add_u64 v[208:209], s[74:75], 0, v[206:207]
	s_add_i32 m0, s28, 0xe000
	s_nop 0
	global_load_lds_dwordx4 v[208:209], off
	s_waitcnt lgkmcnt(8)
	s_barrier
	s_waitcnt lgkmcnt(0)
	s_setprio 1
	s_waitcnt lgkmcnt(0)
	v_mfma_f32_16x16x32_bf16 v[124:127], v[128:131], v[144:147], v[124:127]
	v_mfma_f32_16x16x32_bf16 v[120:123], v[136:139], v[144:147], v[120:123]
	v_mfma_f32_16x16x32_bf16 v[116:119], v[128:131], v[152:155], v[116:119]
	v_mfma_f32_16x16x32_bf16 v[104:107], v[136:139], v[152:155], v[104:107]
	v_mfma_f32_16x16x32_bf16 v[100:103], v[128:131], v[160:163], v[100:103]
	v_mfma_f32_16x16x32_bf16 v[88:91], v[136:139], v[160:163], v[88:91]
	v_mfma_f32_16x16x32_bf16 v[84:87], v[128:131], v[168:171], v[84:87]
	v_mfma_f32_16x16x32_bf16 v[72:75], v[136:139], v[168:171], v[72:75]
	v_mfma_f32_16x16x32_bf16 v[124:127], v[132:135], v[148:151], v[124:127]
	v_mfma_f32_16x16x32_bf16 v[120:123], v[140:143], v[148:151], v[120:123]
	v_mfma_f32_16x16x32_bf16 v[116:119], v[132:135], v[156:159], v[116:119]
	v_mfma_f32_16x16x32_bf16 v[104:107], v[140:143], v[156:159], v[104:107]
	v_mfma_f32_16x16x32_bf16 v[100:103], v[132:135], v[164:167], v[100:103]
	v_mfma_f32_16x16x32_bf16 v[88:91], v[140:143], v[164:167], v[88:91]
	v_mfma_f32_16x16x32_bf16 v[84:87], v[132:135], v[172:175], v[84:87]
	v_mfma_f32_16x16x32_bf16 v[72:75], v[140:143], v[172:175], v[72:75]
	s_setprio 0
	s_barrier
	s_add_i32 s82, s82, s27
	v_add_u32_e32 v180, s95, v189
	v_lshl_add_u64 v[224:225], s[78:79], 0, v[178:179]
	s_mov_b32 m0, s82
	ds_read_b128 v[208:211], v180
	ds_read_b128 v[212:215], v180 offset:1024
	ds_read_b128 v[216:219], v180 offset:2048
	ds_read_b128 v[220:223], v180 offset:3072
	global_load_lds_dwordx4 v[224:225], off
	v_lshl_add_u64 v[226:227], s[78:79], 0, v[186:187]
	s_add_i32 m0, s82, 0x2000
	s_nop 0
	global_load_lds_dwordx4 v[226:227], off
	s_barrier
	s_waitcnt lgkmcnt(0)
	s_setprio 1
	s_waitcnt lgkmcnt(0)
	v_mfma_f32_16x16x32_bf16 v[112:115], v[208:211], v[144:147], v[112:115]
	v_mfma_f32_16x16x32_bf16 v[108:111], v[216:219], v[144:147], v[108:111]
	v_mfma_f32_16x16x32_bf16 v[96:99], v[208:211], v[152:155], v[96:99]
	v_mfma_f32_16x16x32_bf16 v[92:95], v[216:219], v[152:155], v[92:95]
	v_mfma_f32_16x16x32_bf16 v[80:83], v[208:211], v[160:163], v[80:83]
	v_mfma_f32_16x16x32_bf16 v[76:79], v[216:219], v[160:163], v[76:79]
	v_mfma_f32_16x16x32_bf16 v[68:71], v[208:211], v[168:171], v[68:71]
	v_mfma_f32_16x16x32_bf16 v[64:67], v[216:219], v[168:171], v[64:67]
	v_mfma_f32_16x16x32_bf16 v[112:115], v[212:215], v[148:151], v[112:115]
	v_mfma_f32_16x16x32_bf16 v[108:111], v[220:223], v[148:151], v[108:111]
	v_mfma_f32_16x16x32_bf16 v[96:99], v[212:215], v[156:159], v[96:99]
	v_mfma_f32_16x16x32_bf16 v[92:95], v[220:223], v[156:159], v[92:95]
	v_mfma_f32_16x16x32_bf16 v[80:83], v[212:215], v[164:167], v[80:83]
	v_mfma_f32_16x16x32_bf16 v[76:79], v[220:223], v[164:167], v[76:79]
	v_mfma_f32_16x16x32_bf16 v[68:71], v[212:215], v[172:175], v[68:71]
	v_mfma_f32_16x16x32_bf16 v[64:67], v[220:223], v[172:175], v[64:67]
	s_setprio 0
	s_mov_b32 m0, s28
	v_lshl_add_u64 v[228:229], s[76:77], 0, v[176:177]
	s_barrier
	ds_read_b128 v[144:147], v197 offset:16384
	ds_read_b128 v[148:151], v197 offset:17408
	ds_read_b128 v[152:155], v197 offset:18432
	ds_read_b128 v[156:159], v197 offset:19456
	ds_read_b128 v[160:163], v197 offset:20480
	ds_read_b128 v[164:167], v197 offset:21504
	ds_read_b128 v[168:171], v197 offset:22528
	ds_read_b128 v[172:175], v197 offset:23552
	global_load_lds_dwordx4 v[228:229], off
	v_lshl_add_u64 v[242:243], s[76:77], 0, v[184:185]
	s_mov_b32 m0, s34
	s_nop 0
	global_load_lds_dwordx4 v[242:243], off
	s_barrier
	s_waitcnt lgkmcnt(0)
	s_setprio 1
	s_waitcnt lgkmcnt(0)
	v_mfma_f32_16x16x32_bf16 v[60:63], v[128:131], v[144:147], v[60:63]
	v_mfma_f32_16x16x32_bf16 v[56:59], v[136:139], v[144:147], v[56:59]
	v_mfma_f32_16x16x32_bf16 v[52:55], v[128:131], v[152:155], v[52:55]
	v_mfma_f32_16x16x32_bf16 v[40:43], v[136:139], v[152:155], v[40:43]
	v_mfma_f32_16x16x32_bf16 v[36:39], v[128:131], v[160:163], v[36:39]
	v_mfma_f32_16x16x32_bf16 v[16:19], v[136:139], v[160:163], v[16:19]
	v_mfma_f32_16x16x32_bf16 v[12:15], v[128:131], v[168:171], v[12:15]
	v_mfma_f32_16x16x32_bf16 v[0:3], v[136:139], v[168:171], v[0:3]
	v_mfma_f32_16x16x32_bf16 v[60:63], v[132:135], v[148:151], v[60:63]
	v_mfma_f32_16x16x32_bf16 v[56:59], v[140:143], v[148:151], v[56:59]
	v_mfma_f32_16x16x32_bf16 v[52:55], v[132:135], v[156:159], v[52:55]
	v_mfma_f32_16x16x32_bf16 v[40:43], v[140:143], v[156:159], v[40:43]
	v_mfma_f32_16x16x32_bf16 v[36:39], v[132:135], v[164:167], v[36:39]
	v_mfma_f32_16x16x32_bf16 v[16:19], v[140:143], v[164:167], v[16:19]
	v_mfma_f32_16x16x32_bf16 v[12:15], v[132:135], v[172:175], v[12:15]
	v_mfma_f32_16x16x32_bf16 v[0:3], v[140:143], v[172:175], v[0:3]
	s_setprio 0
	s_barrier
; #define PG8_STAGE(bufoff, gbase, voff) do { _Pragma("unroll") for (int _i = 0; _i < 2; ++_i) \
;         __builtin_amdgcn_global_load_lds((const unsigned*)((const char*)(gbase) + (voff)[_i]), (LAS unsigned*)(lds + (bufoff) + ldsw + _i * 8192), 16, 0, 0); } while (0)
; #define PG8_LDA(dst, b, h) do { _Pragma("unroll") for (int m = 0; m < 4; ++m) _Pragma("unroll") for (int k = 0; k < 2; ++k) dst[m][k] = *(const LAS bf16x8*)(lds + PG8_SA(b, h) + aoff + m * 2048 + k * 1024); } while (0)
; #define PG8_LDB(dst, b, h) do { _Pragma("unroll") for (int n = 0; n < 2; ++n) _Pragma("unroll") for (int k = 0; k < 2; ++k) dst[n][k] = *(const LAS bf16x8*)(lds + PG8_SB(b, h) + boff + n * 2048 + k * 1024); } while (0)
; #define PG8_MMA(ai, bj, At, Bt) do { __builtin_amdgcn_s_setprio(1); _Pragma("unroll") for (int m = 0; m < 4; ++m) _Pragma("unroll") for (int n = 0; n < 2; ++n) _Pragma("unroll") for (int k = 0; k < 2; ++k) \
;         acc[ai][bj][m][n] = __builtin_amdgcn_mfma_f32_16x16x32_bf16(Bt[n][k], At[m][k], acc[ai][bj][m][n], 0, 0, 0); __builtin_amdgcn_s_setprio(0); } while (0)
; #define PG8_WAIT_V(n) asm volatile("s_waitcnt vmcnt(" #n ")" ::: "memory")
; #define PG8_WAIT_L(n) asm volatile("s_waitcnt lgkmcnt(" #n ")" ::: "memory")
; #define PG8_BAR __builtin_amdgcn_s_barrier()
; #define PG8_SCHED __builtin_amdgcn_sched_barrier(0)
; template <class F>
; DI void gemm_phase(const int tid, LAS unsigned char* lds, const bf16_t* Ap, int lda, const bf16_t* Bp, int ldb, int M, int N, int K, int G, int c, bool direct, const F& E) {
;     ...
;             PG8_STAGE(PG8_SB(0, 1), b2 + hsB, voffB);
;             PG8_WAIT_V(6); PG8_BAR; PG8_MMA(1, 1, At, B1); PG8_BAR;
;             PG8_LDB(B0, 1, 0); PG8_SCHED; PG8_LDA(At, 1, 0); PG8_STAGE(PG8_SA(0, 1), a2 + hsA, voffA);
;             PG8_WAIT_L(8); PG8_BAR; PG8_WAIT_L(0); PG8_MMA(0, 0, At, B0); PG8_BAR; PG8_SCHED;
;             PG8_LDB(B1, 1, 1); PG8_STAGE(PG8_SB(1, 0), b3, voffB);
;             PG8_BAR; PG8_WAIT_L(0); PG8_MMA(0, 1, At, B1); PG8_BAR;
;             PG8_LDA(At, 1, 1); PG8_STAGE(PG8_SA(1, 0), a3, voffA);
;             PG8_BAR; PG8_WAIT_L(0); PG8_MMA(1, 0, At, B0); PG8_BAR; PG8_SCHED;
	s_add_u32 s78, s78, s46
	s_addc_u32 s79, s79, 0
	s_add_i32 s82, s95, s27
	v_lshl_add_u64 v[244:245], s[78:79], 0, v[178:179]
	s_mov_b32 m0, s82
	v_lshl_add_u64 v[246:247], s[78:79], 0, v[186:187]
	global_load_lds_dwordx4 v[244:245], off
	s_add_i32 m0, s82, 0x2000
	s_nop 0
	global_load_lds_dwordx4 v[246:247], off
	s_waitcnt vmcnt(6)
	s_barrier
	s_setprio 1
	v_mfma_f32_16x16x32_bf16 v[48:51], v[208:211], v[144:147], v[48:51]
	v_mfma_f32_16x16x32_bf16 v[44:47], v[216:219], v[144:147], v[44:47]
	v_mfma_f32_16x16x32_bf16 v[24:27], v[208:211], v[152:155], v[24:27]
	v_mfma_f32_16x16x32_bf16 v[20:23], v[216:219], v[152:155], v[20:23]
	v_mfma_f32_16x16x32_bf16 v[28:31], v[208:211], v[160:163], v[28:31]
	v_mfma_f32_16x16x32_bf16 v[32:35], v[216:219], v[160:163], v[32:35]
	v_mfma_f32_16x16x32_bf16 v[8:11], v[208:211], v[168:171], v[8:11]
	v_mfma_f32_16x16x32_bf16 v[4:7], v[216:219], v[168:171], v[4:7]
	v_mfma_f32_16x16x32_bf16 v[48:51], v[212:215], v[148:151], v[48:51]
	v_mfma_f32_16x16x32_bf16 v[44:47], v[220:223], v[148:151], v[44:47]
	v_mfma_f32_16x16x32_bf16 v[24:27], v[212:215], v[156:159], v[24:27]
	v_mfma_f32_16x16x32_bf16 v[20:23], v[220:223], v[156:159], v[20:23]
	v_mfma_f32_16x16x32_bf16 v[28:31], v[212:215], v[164:167], v[28:31]
	v_mfma_f32_16x16x32_bf16 v[32:35], v[220:223], v[164:167], v[32:35]
	v_mfma_f32_16x16x32_bf16 v[8:11], v[212:215], v[172:175], v[8:11]
	v_mfma_f32_16x16x32_bf16 v[4:7], v[220:223], v[172:175], v[4:7]
	s_setprio 0
	s_add_i32 s78, 0, 0x18000
	v_add_u32_e32 v140, s78, v189
	s_barrier
	ds_read_b128 v[128:131], v140
	ds_read_b128 v[132:135], v140 offset:1024
	ds_read_b128 v[136:139], v140 offset:2048
	ds_read_b128 v[140:143], v140 offset:3072
	s_add_u32 s76, s76, s24
	s_addc_u32 s77, s77, 0
	s_mov_b32 m0, s60
	v_lshl_add_u64 v[208:209], s[76:77], 0, v[176:177]
	ds_read_b128 v[144:147], v197 offset:32768
	ds_read_b128 v[148:151], v197 offset:33792
	ds_read_b128 v[152:155], v197 offset:34816
	ds_read_b128 v[156:159], v197 offset:35840
	ds_read_b128 v[160:163], v197 offset:36864
	ds_read_b128 v[164:167], v197 offset:37888
	ds_read_b128 v[168:171], v197 offset:38912
	ds_read_b128 v[172:175], v197 offset:39936
	global_load_lds_dwordx4 v[208:209], off
	v_lshl_add_u64 v[208:209], s[76:77], 0, v[184:185]
	s_mov_b32 m0, s61
	s_nop 0
	global_load_lds_dwordx4 v[208:209], off
	s_waitcnt lgkmcnt(8)
	s_barrier
	s_waitcnt lgkmcnt(0)
	s_setprio 1
	s_waitcnt lgkmcnt(0)
	v_mfma_f32_16x16x32_bf16 v[124:127], v[128:131], v[144:147], v[124:127]
	v_mfma_f32_16x16x32_bf16 v[120:123], v[136:139], v[144:147], v[120:123]
	v_mfma_f32_16x16x32_bf16 v[116:119], v[128:131], v[152:155], v[116:119]
	v_mfma_f32_16x16x32_bf16 v[104:107], v[136:139], v[152:155], v[104:107]
	v_mfma_f32_16x16x32_bf16 v[100:103], v[128:131], v[160:163], v[100:103]
	v_mfma_f32_16x16x32_bf16 v[88:91], v[136:139], v[160:163], v[88:91]
	v_mfma_f32_16x16x32_bf16 v[84:87], v[128:131], v[168:171], v[84:87]
	v_mfma_f32_16x16x32_bf16 v[72:75], v[136:139], v[168:171], v[72:75]
	v_mfma_f32_16x16x32_bf16 v[124:127], v[132:135], v[148:151], v[124:127]
	v_mfma_f32_16x16x32_bf16 v[120:123], v[140:143], v[148:151], v[120:123]
	v_mfma_f32_16x16x32_bf16 v[116:119], v[132:135], v[156:159], v[116:119]
	v_mfma_f32_16x16x32_bf16 v[104:107], v[140:143], v[156:159], v[104:107]
	v_mfma_f32_16x16x32_bf16 v[100:103], v[132:135], v[164:167], v[100:103]
	v_mfma_f32_16x16x32_bf16 v[88:91], v[140:143], v[164:167], v[88:91]
	v_mfma_f32_16x16x32_bf16 v[84:87], v[132:135], v[172:175], v[84:87]
	v_mfma_f32_16x16x32_bf16 v[72:75], v[140:143], v[172:175], v[72:75]
	s_setprio 0
	s_barrier
	s_add_i32 s76, 0, 0x1c000
	s_add_i32 s77, s78, s27
	v_add_u32_e32 v180, s76, v189
	v_lshl_add_u64 v[224:225], v[224:225], 0, s[30:31]
	s_mov_b32 m0, s77
	ds_read_b128 v[208:211], v180
	ds_read_b128 v[212:215], v180 offset:1024
	ds_read_b128 v[216:219], v180 offset:2048
	ds_read_b128 v[220:223], v180 offset:3072
	global_load_lds_dwordx4 v[224:225], off
	v_lshl_add_u64 v[224:225], v[226:227], 0, s[30:31]
	s_add_i32 m0, s77, 0x2000
	s_nop 0
	global_load_lds_dwordx4 v[224:225], off
	s_barrier
	s_waitcnt lgkmcnt(0)
	s_setprio 1
	s_waitcnt lgkmcnt(0)
	v_mfma_f32_16x16x32_bf16 v[112:115], v[208:211], v[144:147], v[112:115]
	v_mfma_f32_16x16x32_bf16 v[108:111], v[216:219], v[144:147], v[108:111]
	v_mfma_f32_16x16x32_bf16 v[96:99], v[208:211], v[152:155], v[96:99]
	v_mfma_f32_16x16x32_bf16 v[92:95], v[216:219], v[152:155], v[92:95]
	v_mfma_f32_16x16x32_bf16 v[80:83], v[208:211], v[160:163], v[80:83]
	v_mfma_f32_16x16x32_bf16 v[76:79], v[216:219], v[160:163], v[76:79]
	v_mfma_f32_16x16x32_bf16 v[68:71], v[208:211], v[168:171], v[68:71]
	v_mfma_f32_16x16x32_bf16 v[64:67], v[216:219], v[168:171], v[64:67]
	v_mfma_f32_16x16x32_bf16 v[112:115], v[212:215], v[148:151], v[112:115]
	v_mfma_f32_16x16x32_bf16 v[108:111], v[220:223], v[148:151], v[108:111]
	v_mfma_f32_16x16x32_bf16 v[96:99], v[212:215], v[156:159], v[96:99]
	v_mfma_f32_16x16x32_bf16 v[92:95], v[220:223], v[156:159], v[92:95]
	v_mfma_f32_16x16x32_bf16 v[80:83], v[212:215], v[164:167], v[80:83]
	v_mfma_f32_16x16x32_bf16 v[76:79], v[220:223], v[164:167], v[76:79]
	v_mfma_f32_16x16x32_bf16 v[68:71], v[212:215], v[172:175], v[68:71]
	v_mfma_f32_16x16x32_bf16 v[64:67], v[220:223], v[172:175], v[64:67]
	s_setprio 0
	s_mov_b32 m0, s62
	v_lshl_add_u64 v[224:225], v[228:229], 0, s[30:31]
	s_barrier
	ds_read_b128 v[144:147], v197 offset:49152
	ds_read_b128 v[148:151], v197 offset:50176
	ds_read_b128 v[152:155], v197 offset:51200
	ds_read_b128 v[156:159], v197 offset:52224
	ds_read_b128 v[160:163], v197 offset:53248
	ds_read_b128 v[164:167], v197 offset:54272
	ds_read_b128 v[168:171], v197 offset:55296
	ds_read_b128 v[172:175], v197 offset:56320
	global_load_lds_dwordx4 v[224:225], off
	v_lshl_add_u64 v[224:225], v[242:243], 0, s[30:31]
	s_mov_b32 m0, s63
	s_nop 0
	global_load_lds_dwordx4 v[224:225], off
	s_barrier
; #define PG8_STAGE(bufoff, gbase, voff) do { _Pragma("unroll") for (int _i = 0; _i < 2; ++_i) \
;         __builtin_amdgcn_global_load_lds((const unsigned*)((const char*)(gbase) + (voff)[_i]), (LAS unsigned*)(lds + (bufoff) + ldsw + _i * 8192), 16, 0, 0); } while (0)
; #define PG8_MMA(ai, bj, At, Bt) do { __builtin_amdgcn_s_setprio(1); _Pragma("unroll") for (int m = 0; m < 4; ++m) _Pragma("unroll") for (int n = 0; n < 2; ++n) _Pragma("unroll") for (int k = 0; k < 2; ++k) \
;         acc[ai][bj][m][n] = __builtin_amdgcn_mfma_f32_16x16x32_bf16(Bt[n][k], At[m][k], acc[ai][bj][m][n], 0, 0, 0); __builtin_amdgcn_s_setprio(0); } while (0)
; #define PG8_WAIT_V(n) asm volatile("s_waitcnt vmcnt(" #n ")" ::: "memory")
; #define PG8_WAIT_L(n) asm volatile("s_waitcnt lgkmcnt(" #n ")" ::: "memory")
; #define PG8_BAR __builtin_amdgcn_s_barrier()
; #define PG8_SCHED __builtin_amdgcn_sched_barrier(0)
; template <class F>
; DI void gemm_phase(const int tid, LAS unsigned char* lds, const bf16_t* Ap, int lda, const bf16_t* Bp, int ldb, int M, int N, int K, int G, int c, bool direct, const F& E) {
;     ...
;             PG8_BAR; PG8_WAIT_L(0); PG8_MMA(1, 0, At, B0); PG8_BAR; PG8_SCHED;
;             PG8_STAGE(PG8_SB(1, 1), b3 + hsB, voffB);
;             PG8_WAIT_V(6); PG8_BAR; PG8_MMA(1, 1, At, B1); PG8_BAR;
;         }
;         if (E.kind == 7  ) E.fused(acc, cur.pm, cur.pn, wr, wc, fr, fq);
;         else if (E.kind == 3  ) {
	s_waitcnt lgkmcnt(0)
	s_setprio 1
	s_waitcnt lgkmcnt(0)
	v_mfma_f32_16x16x32_bf16 v[60:63], v[128:131], v[144:147], v[60:63]
	v_mfma_f32_16x16x32_bf16 v[56:59], v[136:139], v[144:147], v[56:59]
	v_mfma_f32_16x16x32_bf16 v[52:55], v[128:131], v[152:155], v[52:55]
	v_mfma_f32_16x16x32_bf16 v[40:43], v[136:139], v[152:155], v[40:43]
	v_mfma_f32_16x16x32_bf16 v[36:39], v[128:131], v[160:163], v[36:39]
	v_mfma_f32_16x16x32_bf16 v[16:19], v[136:139], v[160:163], v[16:19]
	v_mfma_f32_16x16x32_bf16 v[12:15], v[128:131], v[168:171], v[12:15]
	v_mfma_f32_16x16x32_bf16 v[0:3], v[136:139], v[168:171], v[0:3]
	v_mfma_f32_16x16x32_bf16 v[60:63], v[132:135], v[148:151], v[60:63]
	v_mfma_f32_16x16x32_bf16 v[56:59], v[140:143], v[148:151], v[56:59]
	v_mfma_f32_16x16x32_bf16 v[52:55], v[132:135], v[156:159], v[52:55]
	v_mfma_f32_16x16x32_bf16 v[40:43], v[140:143], v[156:159], v[40:43]
	v_mfma_f32_16x16x32_bf16 v[36:39], v[132:135], v[164:167], v[36:39]
	v_mfma_f32_16x16x32_bf16 v[16:19], v[140:143], v[164:167], v[16:19]
	v_mfma_f32_16x16x32_bf16 v[12:15], v[132:135], v[172:175], v[12:15]
	v_mfma_f32_16x16x32_bf16 v[0:3], v[140:143], v[172:175], v[0:3]
	s_setprio 0
	s_barrier
	s_add_i32 s76, s76, s27
	v_lshl_add_u64 v[128:129], v[244:245], 0, s[30:31]
	s_mov_b32 m0, s76
	s_nop 0
	global_load_lds_dwordx4 v[128:129], off
	v_lshl_add_u64 v[128:129], v[246:247], 0, s[30:31]
	s_add_i32 m0, s76, 0x2000
	s_nop 0
	global_load_lds_dwordx4 v[128:129], off
	s_waitcnt vmcnt(6)
	s_barrier
	s_setprio 1
	v_mfma_f32_16x16x32_bf16 v[48:51], v[208:211], v[144:147], v[48:51]
	v_mfma_f32_16x16x32_bf16 v[44:47], v[216:219], v[144:147], v[44:47]
	v_mfma_f32_16x16x32_bf16 v[24:27], v[208:211], v[152:155], v[24:27]
	v_mfma_f32_16x16x32_bf16 v[20:23], v[216:219], v[152:155], v[20:23]
	v_mfma_f32_16x16x32_bf16 v[28:31], v[208:211], v[160:163], v[28:31]
	v_mfma_f32_16x16x32_bf16 v[32:35], v[216:219], v[160:163], v[32:35]
	v_mfma_f32_16x16x32_bf16 v[8:11], v[208:211], v[168:171], v[8:11]
	v_mfma_f32_16x16x32_bf16 v[4:7], v[216:219], v[168:171], v[4:7]
	v_mfma_f32_16x16x32_bf16 v[48:51], v[212:215], v[148:151], v[48:51]
	v_mfma_f32_16x16x32_bf16 v[44:47], v[220:223], v[148:151], v[44:47]
	v_mfma_f32_16x16x32_bf16 v[24:27], v[212:215], v[156:159], v[24:27]
	v_mfma_f32_16x16x32_bf16 v[20:23], v[220:223], v[156:159], v[20:23]
	v_mfma_f32_16x16x32_bf16 v[28:31], v[212:215], v[164:167], v[28:31]
	v_mfma_f32_16x16x32_bf16 v[32:35], v[220:223], v[164:167], v[32:35]
	v_mfma_f32_16x16x32_bf16 v[8:11], v[212:215], v[172:175], v[8:11]
	v_mfma_f32_16x16x32_bf16 v[4:7], v[220:223], v[172:175], v[4:7]
	s_setprio 0
	s_add_u32 s74, s74, 0x100
	s_addc_u32 s75, s75, 0
	s_add_u32 s71, s71, 0x100
	s_addc_u32 s80, s80, 0
	s_cmp_ge_u32 s81, s26
	s_mov_b32 s76, s81
	s_barrier
	s_cbranch_scc0 .LBB0_657
	s_mov_b64 s[76:77], -1
	s_mov_b64 s[74:75], 0
	s_cmp_lt_i32 s92, 3
	s_mov_b64 s[78:79], 0
	s_cbranch_scc1 .LBB0_688
	s_cmp_gt_i32 s92, 6
	s_mov_b64 s[78:79], -1
	s_cbranch_scc0 .LBB0_685
; DI float silu_fast(float x) { return x * __builtin_amdgcn_rcpf(1.f + __expf(-x)); }
; template <int CTRL> DI float dppf(float v) { return __builtin_bit_cast(float, __builtin_amdgcn_update_dpp(0, __builtin_bit_cast(int, v), CTRL, 0xf, 0xf, true)); }
; DI void Epi::fused(const f32x4 (&acc)[2][2][4][2], int pm, int pn, int wr, int wc, int fr, int fq) const {
;     ...
;     for (int bj = 0; bj < 2; ++bj) {
;         const int ncol = pn * 256 + bj * 128 + wc * 32 + 8 * fq, j0 = (ncol >> 3) * 4;
;         const f32x4 wa0 = *(const f32x4*)(E.cf0 + j0), wa1 = *(const f32x4*)(E.cf0 + FF2 + j0), wa2 = *(const f32x4*)(E.cf0 + 2 * FF2 + j0);
;         const f32x4 wb0 = *(const f32x4*)(E.cf0 + FFH + j0), wb1 = *(const f32x4*)(E.cf0 + FF2 + FFH + j0), wb2 = *(const f32x4*)(E.cf0 + 2 * FF2 + FFH + j0);
;         const f32x4 ba = *(const f32x4*)(E.cf1 + j0), bb = *(const f32x4*)(E.cf1 + FFH + j0);
; #pragma unroll
;         for (int ai = 0; ai < 2; ++ai) {
;             f32x4 pa = (f32x4){0.f, 0.f, 0.f, 0.f}, pb = pa;
; #pragma unroll
;             for (int m = 0; m < 4; ++m) {
;                 const f32x4 ca = acc[ai][bj][m][0], cb = acc[ai][bj][m][1];
;                 const int row = pm * 256 + ai * 128 + wr * 64 + m * 16 + fr;
;                 float o[4];
; #pragma unroll
;                 for (int e = 0; e < 4; ++e) {
;                     const float a1 = dppf<0x111>(ca[e]) + dppf<0x10F>(pa[e]), a2 = dppf<0x112>(ca[e]) + dppf<0x10E>(pa[e]);
;                     const float b1 = dppf<0x111>(cb[e]) + dppf<0x10F>(pb[e]), b2 = dppf<0x112>(cb[e]) + dppf<0x10E>(pb[e]);
;                     const float ya = fmaf(wa0[e], a2, fmaf(wa1[e], a1, fmaf(wa2[e], ca[e], ba[e])));
;                     const float yb = fmaf(wb0[e], b2, fmaf(wb1[e], b1, fmaf(wb2[e], cb[e], bb[e])));
;                     o[e] = silu_fast(ya) * yb; }
;                 if (m > 0 || fr >= 2) { u32x2 w; w.x = pk2(o[0], o[1]); w.y = pk2(o[2], o[3]); *(u32x2*)(E.d0 + (size_t)row * FFH + j0) = w; }
	v_lshl_or_b32 v160, s70, 8, v194
	v_ashrrev_i32_e32 v172, 1, v160
	v_ashrrev_i32_e32 v173, 31, v172
	v_readlane_b32 s76, v254, 54
	v_lshlrev_b64 v[148:149], 2, v[172:173]
	v_readlane_b32 s77, v254, 55
	v_lshl_add_u64 v[128:129], s[22:23], 0, v[148:149]
	s_lshl_b32 s71, s36, 8
	v_lshl_add_u64 v[130:131], s[76:77], 0, v[148:149]
	v_readlane_b32 s76, v254, 56
	v_readlane_b32 s77, v254, 57
	global_load_dwordx4 v[136:139], v[128:129], off
	global_load_dwordx4 v[140:143], v[130:131], off
	v_lshl_add_u64 v[128:129], s[76:77], 0, v[148:149]
	v_readlane_b32 s76, v255, 4
	v_readlane_b32 s77, v255, 5
	v_mov_b32_dpp v212, v124 row_shr:1 row_mask:0xf bank_mask:0xf bound_ctrl:1
	v_mov_b32_dpp v162, v181 row_shl:15 row_mask:0xf bank_mask:0xf bound_ctrl:1
	v_lshl_add_u64 v[130:131], s[76:77], 0, v[148:149]
	v_readlane_b32 s76, v255, 6
	v_readlane_b32 s77, v255, 7
	global_load_dwordx4 v[152:155], v[128:129], off
	s_nop 0
	global_load_dwordx4 v[128:131], v[130:131], off
	v_lshl_add_u64 v[132:133], s[76:77], 0, v[148:149]
	v_readlane_b32 s76, v255, 8
	v_readlane_b32 s77, v255, 9
	v_mov_b32_dpp v214, v124 row_shr:2 row_mask:0xf bank_mask:0xf bound_ctrl:1
	v_mov_b32_dpp v164, v181 row_shl:14 row_mask:0xf bank_mask:0xf bound_ctrl:1
	v_lshl_add_u64 v[144:145], s[76:77], 0, v[148:149]
	v_readlane_b32 s76, v254, 49
	v_readlane_b32 s77, v254, 50
	global_load_dwordx4 v[132:135], v[132:133], off
	s_nop 0
	global_load_dwordx4 v[144:147], v[144:145], off
	v_lshl_add_u64 v[150:151], s[76:77], 0, v[148:149]
	v_lshl_add_u64 v[148:149], s[72:73], 0, v[148:149]
	global_load_dwordx4 v[156:159], v[150:151], off
	s_nop 0
	global_load_dwordx4 v[148:151], v[148:149], off
	v_readlane_b32 s76, v255, 16
	s_add_i32 s71, s71, s76
	v_or_b32_e32 v199, s71, v188
	v_mov_b32_dpp v208, v120 row_shr:1 row_mask:0xf bank_mask:0xf bound_ctrl:1
	v_mov_b32_dpp v210, v120 row_shr:2 row_mask:0xf bank_mask:0xf bound_ctrl:1
	v_mov_b32_dpp v213, v125 row_shr:1 row_mask:0xf bank_mask:0xf bound_ctrl:1
	v_mov_b32_dpp v215, v125 row_shr:2 row_mask:0xf bank_mask:0xf bound_ctrl:1
	v_mov_b32_dpp v209, v121 row_shr:1 row_mask:0xf bank_mask:0xf bound_ctrl:1
	v_mov_b32_dpp v211, v121 row_shr:2 row_mask:0xf bank_mask:0xf bound_ctrl:1
	v_mov_b32_dpp v170, v126 row_shr:1 row_mask:0xf bank_mask:0xf bound_ctrl:1
	v_mov_b32_dpp v174, v126 row_shr:2 row_mask:0xf bank_mask:0xf bound_ctrl:1
	v_mov_b32_dpp v166, v122 row_shr:1 row_mask:0xf bank_mask:0xf bound_ctrl:1
	v_mov_b32_dpp v168, v122 row_shr:2 row_mask:0xf bank_mask:0xf bound_ctrl:1
	v_mov_b32_dpp v171, v127 row_shr:1 row_mask:0xf bank_mask:0xf bound_ctrl:1
	v_mov_b32_dpp v175, v127 row_shr:2 row_mask:0xf bank_mask:0xf bound_ctrl:1
	v_mov_b32_dpp v167, v123 row_shr:1 row_mask:0xf bank_mask:0xf bound_ctrl:1
	v_mov_b32_dpp v169, v123 row_shr:2 row_mask:0xf bank_mask:0xf bound_ctrl:1
	s_waitcnt vmcnt(0)
	s_and_saveexec_b64 s[76:77], s[38:39]
	s_cbranch_execz .LBB0_662
	v_pk_fma_f32 v[220:221], v[152:153], v[124:125], v[156:157]
	v_pk_add_f32 v[212:213], v[162:163], v[212:213] op_sel_hi:[0,1]
	v_pk_add_f32 v[214:215], v[164:165], v[214:215] op_sel_hi:[0,1]
	v_pk_fma_f32 v[212:213], v[140:141], v[212:213], v[220:221]
	v_pk_add_f32 v[174:175], v[164:165], v[174:175] op_sel_hi:[0,1]
	v_pk_fma_f32 v[212:213], v[136:137], v[214:215], v[212:213]
	v_pk_fma_f32 v[214:215], v[154:155], v[126:127], v[158:159]
	v_mul_f32_e32 v163, 0xbfb8aa3b, v212
	v_mul_f32_e32 v161, 0xbfb8aa3b, v213
	v_exp_f32_e32 v163, v163
	v_exp_f32_e32 v161, v161
	v_pk_add_f32 v[210:211], v[164:165], v[210:211] op_sel_hi:[0,1]
	v_pk_fma_f32 v[216:217], v[146:147], v[122:123], v[150:151]
	v_pk_add_f32 v[170:171], v[162:163], v[170:171] op_sel_hi:[0,1]
	v_add_f32_e32 v161, 1.0, v161
	v_pk_fma_f32 v[170:171], v[142:143], v[170:171], v[214:215]
	v_rcp_f32_e32 v221, v161
	v_add_f32_e32 v161, 1.0, v163
	v_pk_fma_f32 v[170:171], v[138:139], v[174:175], v[170:171]
	v_rcp_f32_e32 v220, v161
	v_mul_f32_e32 v161, 0xbfb8aa3b, v171
	v_exp_f32_e32 v161, v161
	v_pk_add_f32 v[208:209], v[162:163], v[208:209] op_sel_hi:[0,1]
	v_mul_f32_e32 v163, 0xbfb8aa3b, v170
	v_exp_f32_e32 v163, v163
	v_add_f32_e32 v161, 1.0, v161
	v_rcp_f32_e32 v165, v161
	v_pk_fma_f32 v[218:219], v[144:145], v[120:121], v[148:149]
	v_add_f32_e32 v161, 1.0, v163
	v_pk_add_f32 v[162:163], v[162:163], v[166:167] op_sel_hi:[0,1]
	v_pk_add_f32 v[168:169], v[164:165], v[168:169] op_sel_hi:[0,1]
	v_rcp_f32_e32 v164, v161
	v_pk_fma_f32 v[162:163], v[134:135], v[162:163], v[216:217]
	v_pk_fma_f32 v[208:209], v[132:133], v[208:209], v[218:219]
	v_pk_fma_f32 v[162:163], v[130:131], v[168:169], v[162:163]
	v_pk_mul_f32 v[164:165], v[170:171], v[164:165]
	v_pk_fma_f32 v[208:209], v[128:129], v[210:211], v[208:209]
	v_pk_mul_f32 v[162:163], v[162:163], v[164:165]
	v_pk_mul_f32 v[210:211], v[212:213], v[220:221]
	v_cvt_pk_bf16_f32 v175, v162, v163
	v_mov_b64_e32 v[162:163], s[12:13]
	s_movk_i32 s78, 0x1600
	v_pk_mul_f32 v[208:209], v[208:209], v[210:211]
	v_mad_i64_i32 v[162:163], s[78:79], v199, s78, v[162:163]
	v_cvt_pk_bf16_f32 v174, v208, v209
	v_lshl_add_u64 v[162:163], v[172:173], 1, v[162:163]
	global_store_dwordx2 v[162:163], v[174:175], off

; DI float silu_fast(float x) { return x * __builtin_amdgcn_rcpf(1.f + __expf(-x)); }
; template <int CTRL> DI float dppf(float v) { return __builtin_bit_cast(float, __builtin_amdgcn_update_dpp(0, __builtin_bit_cast(int, v), CTRL, 0xf, 0xf, true)); }
; DI void Epi::fused(const f32x4 (&acc)[2][2][4][2], int pm, int pn, int wr, int wc, int fr, int fq) const {
;     ...
;             for (int m = 0; m < 4; ++m) {
;                 const f32x4 ca = acc[ai][bj][m][0], cb = acc[ai][bj][m][1];
;                 const int row = pm * 256 + ai * 128 + wr * 64 + m * 16 + fr;
;                 float o[4];
; #pragma unroll
;                 for (int e = 0; e < 4; ++e) {
;                     const float a1 = dppf<0x111>(ca[e]) + dppf<0x10F>(pa[e]), a2 = dppf<0x112>(ca[e]) + dppf<0x10E>(pa[e]);
;                     const float b1 = dppf<0x111>(cb[e]) + dppf<0x10F>(pb[e]), b2 = dppf<0x112>(cb[e]) + dppf<0x10E>(pb[e]);
;                     const float ya = fmaf(wa0[e], a2, fmaf(wa1[e], a1, fmaf(wa2[e], ca[e], ba[e])));
;                     const float yb = fmaf(wb0[e], b2, fmaf(wb1[e], b1, fmaf(wb2[e], cb[e], bb[e])));
;                     o[e] = silu_fast(ya) * yb; }
;                 if (m > 0 || fr >= 2) { u32x2 w; w.x = pk2(o[0], o[1]); w.y = pk2(o[2], o[3]); *(u32x2*)(E.d0 + (size_t)row * FFH + j0) = w; }
.LBB0_664:
	s_or_b64 exec, exec, s[78:79]
	v_mov_b32_dpp v162, v116 row_shr:1 row_mask:0xf bank_mask:0xf bound_ctrl:1
	v_mov_b32_dpp v164, v124 row_shl:15 row_mask:0xf bank_mask:0xf bound_ctrl:1
	v_mov_b32_dpp v163, v117 row_shr:1 row_mask:0xf bank_mask:0xf bound_ctrl:1
	v_mov_b32_dpp v165, v125 row_shl:15 row_mask:0xf bank_mask:0xf bound_ctrl:1
	v_mov_b32_dpp v166, v116 row_shr:2 row_mask:0xf bank_mask:0xf bound_ctrl:1
	v_mov_b32_dpp v168, v124 row_shl:14 row_mask:0xf bank_mask:0xf bound_ctrl:1
	v_mov_b32_dpp v167, v117 row_shr:2 row_mask:0xf bank_mask:0xf bound_ctrl:1
	v_mov_b32_dpp v169, v125 row_shl:14 row_mask:0xf bank_mask:0xf bound_ctrl:1
	v_pk_add_f32 v[162:163], v[162:163], v[164:165]
	v_pk_fma_f32 v[164:165], v[152:153], v[116:117], v[156:157]
	v_pk_add_f32 v[166:167], v[166:167], v[168:169]
	v_pk_fma_f32 v[162:163], v[140:141], v[162:163], v[164:165]
	v_mov_b32_dpp v170, v104 row_shr:1 row_mask:0xf bank_mask:0xf bound_ctrl:1
	v_pk_fma_f32 v[162:163], v[136:137], v[166:167], v[162:163]
	v_mov_b32_dpp v174, v120 row_shl:15 row_mask:0xf bank_mask:0xf bound_ctrl:1
	v_mul_f32_e32 v164, 0xbfb8aa3b, v163
	v_exp_f32_e32 v166, v164
	v_mov_b32_dpp v208, v104 row_shr:2 row_mask:0xf bank_mask:0xf bound_ctrl:1
	v_mov_b32_dpp v210, v120 row_shl:14 row_mask:0xf bank_mask:0xf bound_ctrl:1
	v_mov_b32_dpp v171, v105 row_shr:1 row_mask:0xf bank_mask:0xf bound_ctrl:1
	v_add_f32_e32 v166, 1.0, v166
	v_rcp_f32_e32 v167, v166
	v_mul_f32_e32 v166, 0xbfb8aa3b, v162
	v_exp_f32_e32 v166, v166
	v_mov_b32_dpp v175, v121 row_shl:15 row_mask:0xf bank_mask:0xf bound_ctrl:1
	v_mov_b32_dpp v209, v105 row_shr:2 row_mask:0xf bank_mask:0xf bound_ctrl:1
	v_mov_b32_dpp v211, v121 row_shl:14 row_mask:0xf bank_mask:0xf bound_ctrl:1
	v_add_f32_e32 v166, 1.0, v166
	v_rcp_f32_e32 v166, v166
	v_pk_add_f32 v[168:169], v[208:209], v[210:211]
	v_pk_add_f32 v[170:171], v[170:171], v[174:175]
	v_pk_fma_f32 v[208:209], v[144:145], v[104:105], v[148:149]
	v_mov_b32_dpp v212, v118 row_shr:1 row_mask:0xf bank_mask:0xf bound_ctrl:1
	v_pk_fma_f32 v[170:171], v[132:133], v[170:171], v[208:209]
	v_mov_b32_dpp v214, v126 row_shl:15 row_mask:0xf bank_mask:0xf bound_ctrl:1
	v_mov_b32_dpp v213, v119 row_shr:1 row_mask:0xf bank_mask:0xf bound_ctrl:1
	v_mov_b32_dpp v215, v127 row_shl:15 row_mask:0xf bank_mask:0xf bound_ctrl:1
	v_pk_fma_f32 v[168:169], v[128:129], v[168:169], v[170:171]
	v_pk_mul_f32 v[162:163], v[162:163], v[166:167]
	v_mov_b32_dpp v216, v118 row_shr:2 row_mask:0xf bank_mask:0xf bound_ctrl:1
	v_mov_b32_dpp v218, v126 row_shl:14 row_mask:0xf bank_mask:0xf bound_ctrl:1
	v_mov_b32_dpp v217, v119 row_shr:2 row_mask:0xf bank_mask:0xf bound_ctrl:1
	v_mov_b32_dpp v219, v127 row_shl:14 row_mask:0xf bank_mask:0xf bound_ctrl:1
	v_pk_fma_f32 v[164:165], v[154:155], v[118:119], v[158:159]
	v_pk_mul_f32 v[162:163], v[168:169], v[162:163]
	v_pk_add_f32 v[168:169], v[212:213], v[214:215]
	v_pk_add_f32 v[166:167], v[216:217], v[218:219]
	v_pk_fma_f32 v[164:165], v[142:143], v[168:169], v[164:165]
	v_mov_b32_dpp v220, v106 row_shr:1 row_mask:0xf bank_mask:0xf bound_ctrl:1
	v_pk_fma_f32 v[164:165], v[138:139], v[166:167], v[164:165]
	v_mov_b32_dpp v222, v122 row_shl:15 row_mask:0xf bank_mask:0xf bound_ctrl:1
	v_mul_f32_e32 v166, 0xbfb8aa3b, v165
	v_exp_f32_e32 v167, v166
	v_cvt_pk_bf16_f32 v166, v162, v163
	v_mul_f32_e32 v162, 0xbfb8aa3b, v164
	v_exp_f32_e32 v162, v162
	v_add_f32_e32 v163, 1.0, v167
	v_rcp_f32_e32 v163, v163
	v_mov_b32_dpp v221, v107 row_shr:1 row_mask:0xf bank_mask:0xf bound_ctrl:1
	v_add_f32_e32 v162, 1.0, v162
	v_rcp_f32_e32 v162, v162
	v_mov_b32_dpp v223, v123 row_shl:15 row_mask:0xf bank_mask:0xf bound_ctrl:1
	v_mov_b32_dpp v224, v106 row_shr:2 row_mask:0xf bank_mask:0xf bound_ctrl:1
	v_mov_b32_dpp v226, v122 row_shl:14 row_mask:0xf bank_mask:0xf bound_ctrl:1
	v_mov_b32_dpp v225, v107 row_shr:2 row_mask:0xf bank_mask:0xf bound_ctrl:1
	v_mov_b32_dpp v227, v123 row_shl:14 row_mask:0xf bank_mask:0xf bound_ctrl:1
	v_pk_fma_f32 v[174:175], v[146:147], v[106:107], v[150:151]
	v_pk_add_f32 v[170:171], v[220:221], v[222:223]
	v_pk_add_f32 v[168:169], v[224:225], v[226:227]
	v_pk_fma_f32 v[170:171], v[134:135], v[170:171], v[174:175]
	v_pk_mul_f32 v[162:163], v[164:165], v[162:163]
	v_pk_fma_f32 v[168:169], v[130:131], v[168:169], v[170:171]
	v_or_b32_e32 v180, 16, v199
	v_pk_mul_f32 v[162:163], v[168:169], v[162:163]
	s_movk_i32 s80, 0x1600
	v_cvt_pk_bf16_f32 v167, v162, v163
	v_mov_b64_e32 v[162:163], s[12:13]
	v_mad_i64_i32 v[164:165], s[78:79], v180, s80, v[162:163]
	v_lshlrev_b64 v[170:171], 1, v[172:173]
	v_lshl_add_u64 v[168:169], v[164:165], 0, v[170:171]
	global_store_dwordx2 v[168:169], v[166:167], off
	v_mov_b32_dpp v166, v100 row_shr:1 row_mask:0xf bank_mask:0xf bound_ctrl:1
	v_mov_b32_dpp v168, v116 row_shl:15 row_mask:0xf bank_mask:0xf bound_ctrl:1
	v_mov_b32_dpp v167, v101 row_shr:1 row_mask:0xf bank_mask:0xf bound_ctrl:1
	v_mov_b32_dpp v169, v117 row_shl:15 row_mask:0xf bank_mask:0xf bound_ctrl:1
	v_mov_b32_dpp v174, v100 row_shr:2 row_mask:0xf bank_mask:0xf bound_ctrl:1
	v_mov_b32_dpp v208, v116 row_shl:14 row_mask:0xf bank_mask:0xf bound_ctrl:1
	v_mov_b32_dpp v175, v101 row_shr:2 row_mask:0xf bank_mask:0xf bound_ctrl:1
	v_mov_b32_dpp v209, v117 row_shl:14 row_mask:0xf bank_mask:0xf bound_ctrl:1
	v_pk_add_f32 v[166:167], v[166:167], v[168:169]
	v_pk_fma_f32 v[168:169], v[152:153], v[100:101], v[156:157]
	v_pk_add_f32 v[174:175], v[174:175], v[208:209]
	v_pk_fma_f32 v[166:167], v[140:141], v[166:167], v[168:169]
	v_mov_b32_dpp v210, v88 row_shr:1 row_mask:0xf bank_mask:0xf bound_ctrl:1
	v_pk_fma_f32 v[166:167], v[136:137], v[174:175], v[166:167]
; DI float silu_fast(float x) { return x * __builtin_amdgcn_rcpf(1.f + __expf(-x)); }
; template <int CTRL> DI float dppf(float v) { return __builtin_bit_cast(float, __builtin_amdgcn_update_dpp(0, __builtin_bit_cast(int, v), CTRL, 0xf, 0xf, true)); }
; DI void Epi::fused(const f32x4 (&acc)[2][2][4][2], int pm, int pn, int wr, int wc, int fr, int fq) const {
;     ...
;             for (int m = 0; m < 4; ++m) {
;                 const f32x4 ca = acc[ai][bj][m][0], cb = acc[ai][bj][m][1];
;                 const int row = pm * 256 + ai * 128 + wr * 64 + m * 16 + fr;
;                 float o[4];
; #pragma unroll
;                 for (int e = 0; e < 4; ++e) {
;                     const float a1 = dppf<0x111>(ca[e]) + dppf<0x10F>(pa[e]), a2 = dppf<0x112>(ca[e]) + dppf<0x10E>(pa[e]);
;                     const float b1 = dppf<0x111>(cb[e]) + dppf<0x10F>(pb[e]), b2 = dppf<0x112>(cb[e]) + dppf<0x10E>(pb[e]);
;                     const float ya = fmaf(wa0[e], a2, fmaf(wa1[e], a1, fmaf(wa2[e], ca[e], ba[e])));
;                     const float yb = fmaf(wb0[e], b2, fmaf(wb1[e], b1, fmaf(wb2[e], cb[e], bb[e])));
;                     o[e] = silu_fast(ya) * yb; }
;                 if (m > 0 || fr >= 2) { u32x2 w; w.x = pk2(o[0], o[1]); w.y = pk2(o[2], o[3]); *(u32x2*)(E.d0 + (size_t)row * FFH + j0) = w; }
;                 if ((m == 0 && fr < 2) || (m == 3 && fr >= 14)) { float* hb = E.f0 + ((size_t)(row >> 6) * 4 + (m == 0 ? fr : fr - 12)) * FF2 + ncol; *(f32x4*)hb = ca; *(f32x4*)(hb + 4) = cb; }
	v_mov_b32_dpp v212, v104 row_shl:15 row_mask:0xf bank_mask:0xf bound_ctrl:1
	v_mul_f32_e32 v168, 0xbfb8aa3b, v167
	v_exp_f32_e32 v174, v168
	v_mov_b32_dpp v214, v88 row_shr:2 row_mask:0xf bank_mask:0xf bound_ctrl:1
	v_mov_b32_dpp v216, v104 row_shl:14 row_mask:0xf bank_mask:0xf bound_ctrl:1
	v_mov_b32_dpp v211, v89 row_shr:1 row_mask:0xf bank_mask:0xf bound_ctrl:1
	v_add_f32_e32 v174, 1.0, v174
	v_rcp_f32_e32 v175, v174
	v_mul_f32_e32 v174, 0xbfb8aa3b, v166
	v_exp_f32_e32 v174, v174
	v_mov_b32_dpp v213, v105 row_shl:15 row_mask:0xf bank_mask:0xf bound_ctrl:1
	v_mov_b32_dpp v215, v89 row_shr:2 row_mask:0xf bank_mask:0xf bound_ctrl:1
	v_mov_b32_dpp v217, v105 row_shl:14 row_mask:0xf bank_mask:0xf bound_ctrl:1
	v_add_f32_e32 v174, 1.0, v174
	v_rcp_f32_e32 v174, v174
	v_pk_add_f32 v[208:209], v[214:215], v[216:217]
	v_pk_add_f32 v[210:211], v[210:211], v[212:213]
	v_pk_fma_f32 v[214:215], v[144:145], v[88:89], v[148:149]
	v_mov_b32_dpp v218, v102 row_shr:1 row_mask:0xf bank_mask:0xf bound_ctrl:1
	v_pk_fma_f32 v[210:211], v[132:133], v[210:211], v[214:215]
	v_mov_b32_dpp v220, v118 row_shl:15 row_mask:0xf bank_mask:0xf bound_ctrl:1
	v_mov_b32_dpp v219, v103 row_shr:1 row_mask:0xf bank_mask:0xf bound_ctrl:1
	v_mov_b32_dpp v221, v119 row_shl:15 row_mask:0xf bank_mask:0xf bound_ctrl:1
	v_pk_fma_f32 v[208:209], v[128:129], v[208:209], v[210:211]
	v_pk_mul_f32 v[166:167], v[166:167], v[174:175]
	v_mov_b32_dpp v222, v102 row_shr:2 row_mask:0xf bank_mask:0xf bound_ctrl:1
	v_mov_b32_dpp v224, v118 row_shl:14 row_mask:0xf bank_mask:0xf bound_ctrl:1
	v_mov_b32_dpp v223, v103 row_shr:2 row_mask:0xf bank_mask:0xf bound_ctrl:1
	v_mov_b32_dpp v225, v119 row_shl:14 row_mask:0xf bank_mask:0xf bound_ctrl:1
	v_pk_fma_f32 v[168:169], v[154:155], v[102:103], v[158:159]
	v_pk_mul_f32 v[166:167], v[208:209], v[166:167]
	v_pk_add_f32 v[208:209], v[218:219], v[220:221]
	v_pk_add_f32 v[174:175], v[222:223], v[224:225]
	v_pk_fma_f32 v[168:169], v[142:143], v[208:209], v[168:169]
	v_mov_b32_dpp v226, v90 row_shr:1 row_mask:0xf bank_mask:0xf bound_ctrl:1
	v_pk_fma_f32 v[168:169], v[138:139], v[174:175], v[168:169]
	v_mov_b32_dpp v228, v106 row_shl:15 row_mask:0xf bank_mask:0xf bound_ctrl:1
	v_mul_f32_e32 v174, 0xbfb8aa3b, v169
	v_exp_f32_e32 v175, v174
	v_cvt_pk_bf16_f32 v174, v166, v167
	v_mul_f32_e32 v166, 0xbfb8aa3b, v168
	v_exp_f32_e32 v166, v166
	v_add_f32_e32 v167, 1.0, v175
	v_rcp_f32_e32 v167, v167
	v_mov_b32_dpp v227, v91 row_shr:1 row_mask:0xf bank_mask:0xf bound_ctrl:1
	v_add_f32_e32 v166, 1.0, v166
	v_rcp_f32_e32 v166, v166
	v_mov_b32_dpp v229, v107 row_shl:15 row_mask:0xf bank_mask:0xf bound_ctrl:1
	v_mov_b32_dpp v242, v90 row_shr:2 row_mask:0xf bank_mask:0xf bound_ctrl:1
	v_mov_b32_dpp v244, v106 row_shl:14 row_mask:0xf bank_mask:0xf bound_ctrl:1
	v_mov_b32_dpp v243, v91 row_shr:2 row_mask:0xf bank_mask:0xf bound_ctrl:1
	v_mov_b32_dpp v245, v107 row_shl:14 row_mask:0xf bank_mask:0xf bound_ctrl:1
	v_pk_fma_f32 v[212:213], v[146:147], v[90:91], v[150:151]
	v_pk_add_f32 v[210:211], v[226:227], v[228:229]
	v_pk_add_f32 v[208:209], v[242:243], v[244:245]
	v_pk_fma_f32 v[210:211], v[134:135], v[210:211], v[212:213]
	v_pk_mul_f32 v[166:167], v[168:169], v[166:167]
	v_pk_fma_f32 v[208:209], v[130:131], v[208:209], v[210:211]
	v_or_b32_e32 v180, 32, v199
	v_pk_mul_f32 v[166:167], v[208:209], v[166:167]
	v_mov_b32_dpp v208, v84 row_shr:2 row_mask:0xf bank_mask:0xf bound_ctrl:1
	v_cvt_pk_bf16_f32 v175, v166, v167
	v_mad_i64_i32 v[166:167], s[78:79], v180, s80, v[162:163]
	v_lshl_add_u64 v[168:169], v[166:167], 0, v[170:171]
	global_store_dwordx2 v[168:169], v[174:175], off
	v_mov_b32_dpp v174, v100 row_shl:15 row_mask:0xf bank_mask:0xf bound_ctrl:1
	v_mov_b32_dpp v168, v84 row_shr:1 row_mask:0xf bank_mask:0xf bound_ctrl:1
	v_mov_b32_dpp v169, v85 row_shr:1 row_mask:0xf bank_mask:0xf bound_ctrl:1
	v_mov_b32_dpp v175, v101 row_shl:15 row_mask:0xf bank_mask:0xf bound_ctrl:1
	v_mov_b32_dpp v210, v100 row_shl:14 row_mask:0xf bank_mask:0xf bound_ctrl:1
	v_mov_b32_dpp v209, v85 row_shr:2 row_mask:0xf bank_mask:0xf bound_ctrl:1
	v_mov_b32_dpp v211, v101 row_shl:14 row_mask:0xf bank_mask:0xf bound_ctrl:1
	v_pk_add_f32 v[168:169], v[168:169], v[174:175]
	v_pk_fma_f32 v[174:175], v[152:153], v[84:85], v[156:157]
	v_pk_add_f32 v[208:209], v[208:209], v[210:211]
	v_pk_fma_f32 v[168:169], v[140:141], v[168:169], v[174:175]
	v_mov_b32_dpp v212, v72 row_shr:1 row_mask:0xf bank_mask:0xf bound_ctrl:1
	v_pk_fma_f32 v[168:169], v[136:137], v[208:209], v[168:169]
	v_mov_b32_dpp v214, v88 row_shl:15 row_mask:0xf bank_mask:0xf bound_ctrl:1
	v_mul_f32_e32 v174, 0xbfb8aa3b, v169
	v_exp_f32_e32 v180, v174
	v_mov_b32_dpp v216, v72 row_shr:2 row_mask:0xf bank_mask:0xf bound_ctrl:1
	v_mov_b32_dpp v218, v88 row_shl:14 row_mask:0xf bank_mask:0xf bound_ctrl:1
	v_mov_b32_dpp v213, v73 row_shr:1 row_mask:0xf bank_mask:0xf bound_ctrl:1
	v_add_f32_e32 v180, 1.0, v180
	v_rcp_f32_e32 v209, v180
	v_mul_f32_e32 v180, 0xbfb8aa3b, v168
	v_exp_f32_e32 v180, v180
	v_mov_b32_dpp v215, v89 row_shl:15 row_mask:0xf bank_mask:0xf bound_ctrl:1
	v_mov_b32_dpp v217, v73 row_shr:2 row_mask:0xf bank_mask:0xf bound_ctrl:1
	v_mov_b32_dpp v219, v89 row_shl:14 row_mask:0xf bank_mask:0xf bound_ctrl:1
	v_add_f32_e32 v180, 1.0, v180
	v_rcp_f32_e32 v208, v180
	v_pk_add_f32 v[210:211], v[216:217], v[218:219]
	v_pk_add_f32 v[212:213], v[212:213], v[214:215]
	v_pk_fma_f32 v[216:217], v[144:145], v[72:73], v[148:149]
	v_mov_b32_dpp v220, v86 row_shr:1 row_mask:0xf bank_mask:0xf bound_ctrl:1
	v_pk_fma_f32 v[212:213], v[132:133], v[212:213], v[216:217]
	v_mov_b32_dpp v222, v102 row_shl:15 row_mask:0xf bank_mask:0xf bound_ctrl:1
; DI float silu_fast(float x) { return x * __builtin_amdgcn_rcpf(1.f + __expf(-x)); }
; template <int CTRL> DI float dppf(float v) { return __builtin_bit_cast(float, __builtin_amdgcn_update_dpp(0, __builtin_bit_cast(int, v), CTRL, 0xf, 0xf, true)); }
; DI void Epi::fused(const f32x4 (&acc)[2][2][4][2], int pm, int pn, int wr, int wc, int fr, int fq) const {
;     ...
;             for (int m = 0; m < 4; ++m) {
;                 const f32x4 ca = acc[ai][bj][m][0], cb = acc[ai][bj][m][1];
;                 const int row = pm * 256 + ai * 128 + wr * 64 + m * 16 + fr;
;                 float o[4];
; #pragma unroll
;                 for (int e = 0; e < 4; ++e) {
;                     const float a1 = dppf<0x111>(ca[e]) + dppf<0x10F>(pa[e]), a2 = dppf<0x112>(ca[e]) + dppf<0x10E>(pa[e]);
;                     const float b1 = dppf<0x111>(cb[e]) + dppf<0x10F>(pb[e]), b2 = dppf<0x112>(cb[e]) + dppf<0x10E>(pb[e]);
;                     const float ya = fmaf(wa0[e], a2, fmaf(wa1[e], a1, fmaf(wa2[e], ca[e], ba[e])));
;                     const float yb = fmaf(wb0[e], b2, fmaf(wb1[e], b1, fmaf(wb2[e], cb[e], bb[e])));
;                     o[e] = silu_fast(ya) * yb; }
;                 if (m > 0 || fr >= 2) { u32x2 w; w.x = pk2(o[0], o[1]); w.y = pk2(o[2], o[3]); *(u32x2*)(E.d0 + (size_t)row * FFH + j0) = w; }
;                 if ((m == 0 && fr < 2) || (m == 3 && fr >= 14)) { float* hb = E.f0 + ((size_t)(row >> 6) * 4 + (m == 0 ? fr : fr - 12)) * FF2 + ncol; *(f32x4*)hb = ca; *(f32x4*)(hb + 4) = cb; }
	v_mov_b32_dpp v221, v87 row_shr:1 row_mask:0xf bank_mask:0xf bound_ctrl:1
	v_mov_b32_dpp v223, v103 row_shl:15 row_mask:0xf bank_mask:0xf bound_ctrl:1
	v_pk_fma_f32 v[210:211], v[128:129], v[210:211], v[212:213]
	v_pk_mul_f32 v[168:169], v[168:169], v[208:209]
	v_mov_b32_dpp v224, v86 row_shr:2 row_mask:0xf bank_mask:0xf bound_ctrl:1
	v_mov_b32_dpp v226, v102 row_shl:14 row_mask:0xf bank_mask:0xf bound_ctrl:1
	v_mov_b32_dpp v225, v87 row_shr:2 row_mask:0xf bank_mask:0xf bound_ctrl:1
	v_mov_b32_dpp v227, v103 row_shl:14 row_mask:0xf bank_mask:0xf bound_ctrl:1
	v_pk_fma_f32 v[174:175], v[154:155], v[86:87], v[158:159]
	v_pk_mul_f32 v[168:169], v[210:211], v[168:169]
	v_pk_add_f32 v[210:211], v[220:221], v[222:223]
	v_pk_add_f32 v[208:209], v[224:225], v[226:227]
	v_pk_fma_f32 v[174:175], v[142:143], v[210:211], v[174:175]
	v_mov_b32_dpp v228, v74 row_shr:1 row_mask:0xf bank_mask:0xf bound_ctrl:1
	v_pk_fma_f32 v[174:175], v[138:139], v[208:209], v[174:175]
	v_cvt_pk_bf16_f32 v208, v168, v169
	v_mul_f32_e32 v180, 0xbfb8aa3b, v175
	v_mul_f32_e32 v168, 0xbfb8aa3b, v174
	v_exp_f32_e32 v180, v180
	v_exp_f32_e32 v168, v168
	v_mov_b32_dpp v242, v90 row_shl:15 row_mask:0xf bank_mask:0xf bound_ctrl:1
	v_mov_b32_dpp v229, v75 row_shr:1 row_mask:0xf bank_mask:0xf bound_ctrl:1
	v_add_f32_e32 v169, 1.0, v180
	v_add_f32_e32 v168, 1.0, v168
	v_rcp_f32_e32 v169, v169
	v_rcp_f32_e32 v168, v168
	v_mov_b32_dpp v243, v91 row_shl:15 row_mask:0xf bank_mask:0xf bound_ctrl:1
	v_mov_b32_dpp v244, v74 row_shr:2 row_mask:0xf bank_mask:0xf bound_ctrl:1
	v_mov_b32_dpp v246, v90 row_shl:14 row_mask:0xf bank_mask:0xf bound_ctrl:1
	v_mov_b32_dpp v245, v75 row_shr:2 row_mask:0xf bank_mask:0xf bound_ctrl:1
	v_mov_b32_dpp v247, v91 row_shl:14 row_mask:0xf bank_mask:0xf bound_ctrl:1
	v_pk_fma_f32 v[214:215], v[146:147], v[74:75], v[150:151]
	v_pk_add_f32 v[212:213], v[228:229], v[242:243]
	v_pk_add_f32 v[210:211], v[244:245], v[246:247]
	v_pk_fma_f32 v[212:213], v[134:135], v[212:213], v[214:215]
	v_pk_mul_f32 v[168:169], v[174:175], v[168:169]
	v_pk_fma_f32 v[210:211], v[130:131], v[210:211], v[212:213]
	v_or_b32_e32 v201, 48, v199
	v_pk_mul_f32 v[168:169], v[210:211], v[168:169]
	s_movk_i32 s81, 0x1600
	v_cvt_pk_bf16_f32 v209, v168, v169
	v_mad_i64_i32 v[168:169], s[78:79], v201, s80, v[162:163]
	v_lshl_add_u64 v[162:163], v[168:169], 0, v[170:171]
	global_store_dwordx2 v[162:163], v[208:209], off
	v_lshl_add_u64 v[162:163], s[76:77], 0, v[190:191]
	s_and_saveexec_b64 s[76:77], s[42:43]
	s_cbranch_execz .LBB0_666
	v_mov_b64_e32 v[174:175], s[8:9]
	s_movk_i32 s80, 0x5800
	v_mad_u64_u32 v[174:175], s[78:79], v162, s80, v[174:175]
	v_mad_i32_i24 v175, v163, s80, v175
	v_lshl_add_u64 v[174:175], v[160:161], 2, v[174:175]
	global_store_dwordx4 v[174:175], v[84:87], off
	global_store_dwordx4 v[174:175], v[72:75], off offset:16
; DI float silu_fast(float x) { return x * __builtin_amdgcn_rcpf(1.f + __expf(-x)); }
; template <int CTRL> DI float dppf(float v) { return __builtin_bit_cast(float, __builtin_amdgcn_update_dpp(0, __builtin_bit_cast(int, v), CTRL, 0xf, 0xf, true)); }
; DI void Epi::fused(const f32x4 (&acc)[2][2][4][2], int pm, int pn, int wr, int wc, int fr, int fq) const {
;     ...
;     for (int bj = 0; bj < 2; ++bj) {
;         const int ncol = pn * 256 + bj * 128 + wc * 32 + 8 * fq, j0 = (ncol >> 3) * 4;
;         const f32x4 wa0 = *(const f32x4*)(E.cf0 + j0), wa1 = *(const f32x4*)(E.cf0 + FF2 + j0), wa2 = *(const f32x4*)(E.cf0 + 2 * FF2 + j0);
;         const f32x4 wb0 = *(const f32x4*)(E.cf0 + FFH + j0), wb1 = *(const f32x4*)(E.cf0 + FF2 + FFH + j0), wb2 = *(const f32x4*)(E.cf0 + 2 * FF2 + FFH + j0);
;         const f32x4 ba = *(const f32x4*)(E.cf1 + j0), bb = *(const f32x4*)(E.cf1 + FFH + j0);
; #pragma unroll
;         for (int ai = 0; ai < 2; ++ai) {
;             f32x4 pa = (f32x4){0.f, 0.f, 0.f, 0.f}, pb = pa;
; #pragma unroll
;             for (int m = 0; m < 4; ++m) {
;                 const f32x4 ca = acc[ai][bj][m][0], cb = acc[ai][bj][m][1];
;                 const int row = pm * 256 + ai * 128 + wr * 64 + m * 16 + fr;
;                 float o[4];
; #pragma unroll
;                 for (int e = 0; e < 4; ++e) {
;                     const float a1 = dppf<0x111>(ca[e]) + dppf<0x10F>(pa[e]), a2 = dppf<0x112>(ca[e]) + dppf<0x10E>(pa[e]);
;                     const float b1 = dppf<0x111>(cb[e]) + dppf<0x10F>(pb[e]), b2 = dppf<0x112>(cb[e]) + dppf<0x10E>(pb[e]);
;                     const float ya = fmaf(wa0[e], a2, fmaf(wa1[e], a1, fmaf(wa2[e], ca[e], ba[e])));
;                     const float yb = fmaf(wb0[e], b2, fmaf(wb1[e], b1, fmaf(wb2[e], cb[e], bb[e])));
;                     o[e] = silu_fast(ya) * yb; }
.LBB0_666:
	s_or_b64 exec, exec, s[76:77]
	s_addk_i32 s71, 0x80
	v_or_b32_e32 v201, s71, v188
	v_mov_b32_dpp v220, v60 row_shr:1 row_mask:0xf bank_mask:0xf bound_ctrl:1
	v_mov_b32_dpp v174, v181 row_shl:15 row_mask:0xf bank_mask:0xf bound_ctrl:1
	v_mov_b32_dpp v222, v60 row_shr:2 row_mask:0xf bank_mask:0xf bound_ctrl:1
	v_mov_b32_dpp v180, v181 row_shl:14 row_mask:0xf bank_mask:0xf bound_ctrl:1
	v_mov_b32_dpp v216, v56 row_shr:1 row_mask:0xf bank_mask:0xf bound_ctrl:1
	v_mov_b32_dpp v218, v56 row_shr:2 row_mask:0xf bank_mask:0xf bound_ctrl:1
	v_mov_b32_dpp v221, v61 row_shr:1 row_mask:0xf bank_mask:0xf bound_ctrl:1
	v_mov_b32_dpp v223, v61 row_shr:2 row_mask:0xf bank_mask:0xf bound_ctrl:1
	v_mov_b32_dpp v217, v57 row_shr:1 row_mask:0xf bank_mask:0xf bound_ctrl:1
	v_mov_b32_dpp v219, v57 row_shr:2 row_mask:0xf bank_mask:0xf bound_ctrl:1
	v_mov_b32_dpp v212, v62 row_shr:1 row_mask:0xf bank_mask:0xf bound_ctrl:1
	v_mov_b32_dpp v214, v62 row_shr:2 row_mask:0xf bank_mask:0xf bound_ctrl:1
	v_mov_b32_dpp v208, v58 row_shr:1 row_mask:0xf bank_mask:0xf bound_ctrl:1
	v_mov_b32_dpp v210, v58 row_shr:2 row_mask:0xf bank_mask:0xf bound_ctrl:1
	v_mov_b32_dpp v213, v63 row_shr:1 row_mask:0xf bank_mask:0xf bound_ctrl:1
	v_mov_b32_dpp v215, v63 row_shr:2 row_mask:0xf bank_mask:0xf bound_ctrl:1
	v_mov_b32_dpp v209, v59 row_shr:1 row_mask:0xf bank_mask:0xf bound_ctrl:1
	v_mov_b32_dpp v211, v59 row_shr:2 row_mask:0xf bank_mask:0xf bound_ctrl:1
	v_or_b32_e32 v72, 0x80, v160
	v_ashrrev_i32_e32 v72, 1, v72
	v_ashrrev_i32_e32 v73, 31, v72
	v_lshlrev_b64 v[72:73], 2, v[72:73]
	v_lshl_add_u64 v[84:85], s[22:23], 0, v[72:73]
	global_load_dwordx4 v[84:87], v[84:85], off
	v_readlane_b32 s76, v254, 54
	v_readlane_b32 s77, v254, 55
	s_nop 1
	v_lshl_add_u64 v[88:89], s[76:77], 0, v[72:73]
	global_load_dwordx4 v[88:91], v[88:89], off
	v_readlane_b32 s76, v254, 56
	v_readlane_b32 s77, v254, 57
	s_nop 1
	v_lshl_add_u64 v[100:101], s[76:77], 0, v[72:73]
	global_load_dwordx4 v[100:103], v[100:101], off
	v_readlane_b32 s76, v255, 4
	v_readlane_b32 s77, v255, 5
	s_nop 1
	v_lshl_add_u64 v[104:105], s[76:77], 0, v[72:73]
	global_load_dwordx4 v[104:107], v[104:105], off
	v_readlane_b32 s76, v255, 6
	v_readlane_b32 s77, v255, 7
	s_nop 1
	v_lshl_add_u64 v[116:117], s[76:77], 0, v[72:73]
	global_load_dwordx4 v[116:119], v[116:117], off
	v_readlane_b32 s76, v255, 8
	v_readlane_b32 s77, v255, 9
	s_nop 1
	v_lshl_add_u64 v[120:121], s[76:77], 0, v[72:73]
	global_load_dwordx4 v[120:123], v[120:121], off
	v_readlane_b32 s76, v254, 49
	v_readlane_b32 s77, v254, 50
	s_nop 1
	v_lshl_add_u64 v[124:125], s[76:77], 0, v[72:73]
	global_load_dwordx4 v[124:127], v[124:125], off
	v_lshl_add_u64 v[72:73], s[72:73], 0, v[72:73]
	global_load_dwordx4 v[72:75], v[72:73], off
	s_and_saveexec_b64 s[76:77], s[38:39]
	s_cbranch_execz .LBB0_668
	v_pk_fma_f32 v[228:229], v[152:153], v[60:61], v[156:157]
	v_pk_add_f32 v[220:221], v[174:175], v[220:221] op_sel_hi:[0,1]
	v_pk_add_f32 v[222:223], v[180:181], v[222:223] op_sel_hi:[0,1]
	v_pk_fma_f32 v[220:221], v[140:141], v[220:221], v[228:229]
	v_pk_add_f32 v[214:215], v[180:181], v[214:215] op_sel_hi:[0,1]
	v_pk_fma_f32 v[220:221], v[136:137], v[222:223], v[220:221]
	v_pk_fma_f32 v[222:223], v[154:155], v[62:63], v[158:159]
	v_mul_f32_e32 v175, 0xbfb8aa3b, v221
	v_exp_f32_e32 v175, v175
	v_mul_f32_e32 v202, 0xbfb8aa3b, v220
	v_exp_f32_e32 v202, v202
	v_pk_fma_f32 v[226:227], v[144:145], v[56:57], v[148:149]
	v_add_f32_e32 v175, 1.0, v175
	v_rcp_f32_e32 v229, v175
	v_add_f32_e32 v175, 1.0, v202
	v_pk_add_f32 v[212:213], v[174:175], v[212:213] op_sel_hi:[0,1]
	v_pk_fma_f32 v[212:213], v[142:143], v[212:213], v[222:223]
	v_rcp_f32_e32 v228, v175
	v_pk_fma_f32 v[212:213], v[138:139], v[214:215], v[212:213]
	v_pk_add_f32 v[216:217], v[174:175], v[216:217] op_sel_hi:[0,1]
	v_mul_f32_e32 v175, 0xbfb8aa3b, v213
	v_exp_f32_e32 v175, v175
	v_mul_f32_e32 v202, 0xbfb8aa3b, v212
	v_exp_f32_e32 v202, v202
	v_pk_add_f32 v[218:219], v[180:181], v[218:219] op_sel_hi:[0,1]
	v_pk_fma_f32 v[216:217], v[132:133], v[216:217], v[226:227]
	v_add_f32_e32 v175, 1.0, v175
	v_pk_fma_f32 v[216:217], v[128:129], v[218:219], v[216:217]
	v_pk_mul_f32 v[218:219], v[220:221], v[228:229]
	v_pk_fma_f32 v[224:225], v[146:147], v[58:59], v[150:151]
	v_pk_mul_f32 v[216:217], v[216:217], v[218:219]
	v_pk_add_f32 v[210:211], v[180:181], v[210:211] op_sel_hi:[0,1]
	v_cvt_pk_bf16_f32 v214, v216, v217
	v_rcp_f32_e32 v217, v175
	v_add_f32_e32 v175, 1.0, v202
	v_rcp_f32_e32 v216, v175
	v_pk_add_f32 v[174:175], v[174:175], v[208:209] op_sel_hi:[0,1]
	v_pk_fma_f32 v[174:175], v[134:135], v[174:175], v[224:225]
	v_pk_mul_f32 v[208:209], v[212:213], v[216:217]
	v_pk_fma_f32 v[174:175], v[130:131], v[210:211], v[174:175]
	s_nop 0
	v_pk_mul_f32 v[174:175], v[174:175], v[208:209]
	s_nop 0
	v_cvt_pk_bf16_f32 v215, v174, v175
	v_mov_b64_e32 v[174:175], s[12:13]
	v_mad_i64_i32 v[174:175], s[78:79], v201, s81, v[174:175]
	v_lshl_add_u64 v[172:173], v[172:173], 1, v[174:175]
	global_store_dwordx2 v[172:173], v[214:215], off

; DI float silu_fast(float x) { return x * __builtin_amdgcn_rcpf(1.f + __expf(-x)); }
; template <int CTRL> DI float dppf(float v) { return __builtin_bit_cast(float, __builtin_amdgcn_update_dpp(0, __builtin_bit_cast(int, v), CTRL, 0xf, 0xf, true)); }
; DI void Epi::fused(const f32x4 (&acc)[2][2][4][2], int pm, int pn, int wr, int wc, int fr, int fq) const {
;     ...
;     for (int bj = 0; bj < 2; ++bj) {
;         const int ncol = pn * 256 + bj * 128 + wc * 32 + 8 * fq, j0 = (ncol >> 3) * 4;
;         const f32x4 wa0 = *(const f32x4*)(E.cf0 + j0), wa1 = *(const f32x4*)(E.cf0 + FF2 + j0), wa2 = *(const f32x4*)(E.cf0 + 2 * FF2 + j0);
;         const f32x4 wb0 = *(const f32x4*)(E.cf0 + FFH + j0), wb1 = *(const f32x4*)(E.cf0 + FF2 + FFH + j0), wb2 = *(const f32x4*)(E.cf0 + 2 * FF2 + FFH + j0);
;         const f32x4 ba = *(const f32x4*)(E.cf1 + j0), bb = *(const f32x4*)(E.cf1 + FFH + j0);
; #pragma unroll
;         for (int ai = 0; ai < 2; ++ai) {
;             f32x4 pa = (f32x4){0.f, 0.f, 0.f, 0.f}, pb = pa;
; #pragma unroll
;             for (int m = 0; m < 4; ++m) {
;                 const f32x4 ca = acc[ai][bj][m][0], cb = acc[ai][bj][m][1];
;                 const int row = pm * 256 + ai * 128 + wr * 64 + m * 16 + fr;
;                 float o[4];
; #pragma unroll
;                 for (int e = 0; e < 4; ++e) {
;                     const float a1 = dppf<0x111>(ca[e]) + dppf<0x10F>(pa[e]), a2 = dppf<0x112>(ca[e]) + dppf<0x10E>(pa[e]);
;                     const float b1 = dppf<0x111>(cb[e]) + dppf<0x10F>(pb[e]), b2 = dppf<0x112>(cb[e]) + dppf<0x10E>(pb[e]);
;                     const float ya = fmaf(wa0[e], a2, fmaf(wa1[e], a1, fmaf(wa2[e], ca[e], ba[e])));
;                     const float yb = fmaf(wb0[e], b2, fmaf(wb1[e], b1, fmaf(wb2[e], cb[e], bb[e])));
;                     o[e] = silu_fast(ya) * yb; }
;                 if (m > 0 || fr >= 2) { u32x2 w; w.x = pk2(o[0], o[1]); w.y = pk2(o[2], o[3]); *(u32x2*)(E.d0 + (size_t)row * FFH + j0) = w; }
.LBB0_672:
	s_or_b64 exec, exec, s[76:77]
	v_or_b32_e32 v128, 0x80, v160
	v_ashrrev_i32_e32 v212, 1, v128
	v_ashrrev_i32_e32 v213, 31, v212
	v_mov_b32_dpp v226, v112 row_shr:1 row_mask:0xf bank_mask:0xf bound_ctrl:1
	v_mov_b32_dpp v180, v181 row_shl:15 row_mask:0xf bank_mask:0xf bound_ctrl:1
	v_mov_b32_dpp v228, v112 row_shr:2 row_mask:0xf bank_mask:0xf bound_ctrl:1
	v_mov_b32_dpp v210, v181 row_shl:14 row_mask:0xf bank_mask:0xf bound_ctrl:1
	v_mov_b32_dpp v222, v108 row_shr:1 row_mask:0xf bank_mask:0xf bound_ctrl:1
	v_mov_b32_dpp v224, v108 row_shr:2 row_mask:0xf bank_mask:0xf bound_ctrl:1
	v_mov_b32_dpp v227, v113 row_shr:1 row_mask:0xf bank_mask:0xf bound_ctrl:1
	v_mov_b32_dpp v229, v113 row_shr:2 row_mask:0xf bank_mask:0xf bound_ctrl:1
	v_mov_b32_dpp v223, v109 row_shr:1 row_mask:0xf bank_mask:0xf bound_ctrl:1
	v_mov_b32_dpp v225, v109 row_shr:2 row_mask:0xf bank_mask:0xf bound_ctrl:1
	v_mov_b32_dpp v218, v114 row_shr:1 row_mask:0xf bank_mask:0xf bound_ctrl:1
	v_mov_b32_dpp v220, v114 row_shr:2 row_mask:0xf bank_mask:0xf bound_ctrl:1
	v_mov_b32_dpp v214, v110 row_shr:1 row_mask:0xf bank_mask:0xf bound_ctrl:1
	v_mov_b32_dpp v216, v110 row_shr:2 row_mask:0xf bank_mask:0xf bound_ctrl:1
	v_mov_b32_dpp v219, v115 row_shr:1 row_mask:0xf bank_mask:0xf bound_ctrl:1
	v_mov_b32_dpp v221, v115 row_shr:2 row_mask:0xf bank_mask:0xf bound_ctrl:1
	v_mov_b32_dpp v215, v111 row_shr:1 row_mask:0xf bank_mask:0xf bound_ctrl:1
	v_mov_b32_dpp v217, v111 row_shr:2 row_mask:0xf bank_mask:0xf bound_ctrl:1
	s_waitcnt vmcnt(8)
	s_and_saveexec_b64 s[76:77], s[38:39]
	s_cbranch_execz .LBB0_674
	v_pk_fma_f32 v[240:241], v[100:101], v[112:113], v[124:125]
	v_pk_add_f32 v[226:227], v[180:181], v[226:227] op_sel_hi:[0,1]
	v_pk_add_f32 v[228:229], v[210:211], v[228:229] op_sel_hi:[0,1]
	v_pk_fma_f32 v[226:227], v[88:89], v[226:227], v[240:241]
	v_pk_add_f32 v[218:219], v[180:181], v[218:219] op_sel_hi:[0,1]
	v_pk_fma_f32 v[226:227], v[84:85], v[228:229], v[226:227]
	v_pk_fma_f32 v[228:229], v[102:103], v[114:115], v[126:127]
	v_mul_f32_e32 v202, 0xbfb8aa3b, v227
	v_mul_f32_e32 v211, 0xbfb8aa3b, v226
	v_exp_f32_e32 v202, v202
	v_exp_f32_e32 v211, v211
	v_pk_fma_f32 v[218:219], v[90:91], v[218:219], v[228:229]
	v_pk_fma_f32 v[232:233], v[122:123], v[110:111], v[74:75]
	v_add_f32_e32 v202, 1.0, v202
	v_pk_add_f32 v[220:221], v[210:211], v[220:221] op_sel_hi:[0,1]
	v_rcp_f32_e32 v241, v202
	v_add_f32_e32 v202, 1.0, v211
	v_pk_fma_f32 v[218:219], v[86:87], v[220:221], v[218:219]
	v_rcp_f32_e32 v240, v202
	v_mul_f32_e32 v202, 0xbfb8aa3b, v219
	v_exp_f32_e32 v202, v202
	v_pk_add_f32 v[224:225], v[210:211], v[224:225] op_sel_hi:[0,1]
	v_mul_f32_e32 v211, 0xbfb8aa3b, v218
	v_exp_f32_e32 v221, v211
	v_add_f32_e32 v202, 1.0, v202
	v_rcp_f32_e32 v211, v202
	v_pk_add_f32 v[214:215], v[180:181], v[214:215] op_sel_hi:[0,1]
	v_add_f32_e32 v202, 1.0, v221
	v_pk_fma_f32 v[214:215], v[118:119], v[214:215], v[232:233]
	v_pk_add_f32 v[216:217], v[210:211], v[216:217] op_sel_hi:[0,1]
	v_rcp_f32_e32 v210, v202
	v_pk_fma_f32 v[238:239], v[120:121], v[108:109], v[72:73]
	v_pk_add_f32 v[222:223], v[180:181], v[222:223] op_sel_hi:[0,1]
	v_pk_fma_f32 v[214:215], v[106:107], v[216:217], v[214:215]
	v_pk_mul_f32 v[210:211], v[218:219], v[210:211]
	v_pk_fma_f32 v[222:223], v[116:117], v[222:223], v[238:239]
	v_pk_mul_f32 v[210:211], v[214:215], v[210:211]
	v_pk_fma_f32 v[222:223], v[104:105], v[224:225], v[222:223]
	v_pk_mul_f32 v[224:225], v[226:227], v[240:241]
	v_cvt_pk_bf16_f32 v221, v210, v211
	v_mov_b64_e32 v[210:211], s[12:13]
	s_movk_i32 s71, 0x1600
	v_pk_mul_f32 v[222:223], v[222:223], v[224:225]
	v_mad_i64_i32 v[210:211], s[78:79], v199, s71, v[210:211]
	v_cvt_pk_bf16_f32 v220, v222, v223
	v_lshl_add_u64 v[210:211], v[212:213], 1, v[210:211]
	global_store_dwordx2 v[210:211], v[220:221], off

; DI float silu_fast(float x) { return x * __builtin_amdgcn_rcpf(1.f + __expf(-x)); }
; template <int CTRL> DI float dppf(float v) { return __builtin_bit_cast(float, __builtin_amdgcn_update_dpp(0, __builtin_bit_cast(int, v), CTRL, 0xf, 0xf, true)); }
; DI void Epi::fused(const f32x4 (&acc)[2][2][4][2], int pm, int pn, int wr, int wc, int fr, int fq) const {
;     ...
;             for (int m = 0; m < 4; ++m) {
;                 const f32x4 ca = acc[ai][bj][m][0], cb = acc[ai][bj][m][1];
;                 const int row = pm * 256 + ai * 128 + wr * 64 + m * 16 + fr;
;                 float o[4];
; #pragma unroll
;                 for (int e = 0; e < 4; ++e) {
;                     const float a1 = dppf<0x111>(ca[e]) + dppf<0x10F>(pa[e]), a2 = dppf<0x112>(ca[e]) + dppf<0x10E>(pa[e]);
;                     const float b1 = dppf<0x111>(cb[e]) + dppf<0x10F>(pb[e]), b2 = dppf<0x112>(cb[e]) + dppf<0x10E>(pb[e]);
;                     const float ya = fmaf(wa0[e], a2, fmaf(wa1[e], a1, fmaf(wa2[e], ca[e], ba[e])));
;                     const float yb = fmaf(wb0[e], b2, fmaf(wb1[e], b1, fmaf(wb2[e], cb[e], bb[e])));
;                     o[e] = silu_fast(ya) * yb; }
;                 if (m > 0 || fr >= 2) { u32x2 w; w.x = pk2(o[0], o[1]); w.y = pk2(o[2], o[3]); *(u32x2*)(E.d0 + (size_t)row * FFH + j0) = w; }
;                 if ((m == 0 && fr < 2) || (m == 3 && fr >= 14)) { float* hb = E.f0 + ((size_t)(row >> 6) * 4 + (m == 0 ? fr : fr - 12)) * FF2 + ncol; *(f32x4*)hb = ca; *(f32x4*)(hb + 4) = cb; }
.LBB0_676:
	s_or_b64 exec, exec, s[76:77]
	v_mov_b32_dpp v210, v96 row_shr:1 row_mask:0xf bank_mask:0xf bound_ctrl:1
	v_mov_b32_dpp v214, v112 row_shl:15 row_mask:0xf bank_mask:0xf bound_ctrl:1
	v_mov_b32_dpp v211, v97 row_shr:1 row_mask:0xf bank_mask:0xf bound_ctrl:1
	v_mov_b32_dpp v215, v113 row_shl:15 row_mask:0xf bank_mask:0xf bound_ctrl:1
	v_mov_b32_dpp v216, v96 row_shr:2 row_mask:0xf bank_mask:0xf bound_ctrl:1
	v_mov_b32_dpp v218, v112 row_shl:14 row_mask:0xf bank_mask:0xf bound_ctrl:1
	v_mov_b32_dpp v217, v97 row_shr:2 row_mask:0xf bank_mask:0xf bound_ctrl:1
	v_mov_b32_dpp v219, v113 row_shl:14 row_mask:0xf bank_mask:0xf bound_ctrl:1
	v_pk_add_f32 v[210:211], v[210:211], v[214:215]
	v_pk_fma_f32 v[214:215], v[100:101], v[96:97], v[124:125]
	v_pk_add_f32 v[216:217], v[216:217], v[218:219]
	v_pk_fma_f32 v[210:211], v[88:89], v[210:211], v[214:215]
	v_mov_b32_dpp v220, v92 row_shr:1 row_mask:0xf bank_mask:0xf bound_ctrl:1
	v_pk_fma_f32 v[210:211], v[84:85], v[216:217], v[210:211]
	v_mov_b32_dpp v222, v108 row_shl:15 row_mask:0xf bank_mask:0xf bound_ctrl:1
	v_mul_f32_e32 v180, 0xbfb8aa3b, v211
	v_exp_f32_e32 v180, v180
	v_mov_b32_dpp v224, v92 row_shr:2 row_mask:0xf bank_mask:0xf bound_ctrl:1
	v_mov_b32_dpp v226, v108 row_shl:14 row_mask:0xf bank_mask:0xf bound_ctrl:1
	v_mov_b32_dpp v221, v93 row_shr:1 row_mask:0xf bank_mask:0xf bound_ctrl:1
	v_add_f32_e32 v180, 1.0, v180
	v_rcp_f32_e32 v217, v180
	v_mul_f32_e32 v180, 0xbfb8aa3b, v210
	v_exp_f32_e32 v180, v180
	v_mov_b32_dpp v223, v109 row_shl:15 row_mask:0xf bank_mask:0xf bound_ctrl:1
	v_mov_b32_dpp v225, v93 row_shr:2 row_mask:0xf bank_mask:0xf bound_ctrl:1
	v_mov_b32_dpp v227, v109 row_shl:14 row_mask:0xf bank_mask:0xf bound_ctrl:1
	v_add_f32_e32 v180, 1.0, v180
	v_rcp_f32_e32 v216, v180
	v_pk_add_f32 v[218:219], v[224:225], v[226:227]
	v_pk_add_f32 v[220:221], v[220:221], v[222:223]
	v_pk_fma_f32 v[224:225], v[120:121], v[92:93], v[72:73]
	v_mov_b32_dpp v228, v98 row_shr:1 row_mask:0xf bank_mask:0xf bound_ctrl:1
	v_pk_fma_f32 v[220:221], v[116:117], v[220:221], v[224:225]
	v_mov_b32_dpp v232, v114 row_shl:15 row_mask:0xf bank_mask:0xf bound_ctrl:1
	v_mov_b32_dpp v229, v99 row_shr:1 row_mask:0xf bank_mask:0xf bound_ctrl:1
	v_mov_b32_dpp v233, v115 row_shl:15 row_mask:0xf bank_mask:0xf bound_ctrl:1
	v_pk_fma_f32 v[218:219], v[104:105], v[218:219], v[220:221]
	v_pk_mul_f32 v[210:211], v[210:211], v[216:217]
	v_mov_b32_dpp v238, v98 row_shr:2 row_mask:0xf bank_mask:0xf bound_ctrl:1
	v_mov_b32_dpp v240, v114 row_shl:14 row_mask:0xf bank_mask:0xf bound_ctrl:1
	v_mov_b32_dpp v239, v99 row_shr:2 row_mask:0xf bank_mask:0xf bound_ctrl:1
	v_mov_b32_dpp v241, v115 row_shl:14 row_mask:0xf bank_mask:0xf bound_ctrl:1
	v_pk_fma_f32 v[214:215], v[102:103], v[98:99], v[126:127]
	v_pk_mul_f32 v[210:211], v[218:219], v[210:211]
	v_pk_add_f32 v[218:219], v[228:229], v[232:233]
	v_pk_add_f32 v[216:217], v[238:239], v[240:241]
	v_pk_fma_f32 v[214:215], v[90:91], v[218:219], v[214:215]
	v_mov_b32_dpp v244, v94 row_shr:1 row_mask:0xf bank_mask:0xf bound_ctrl:1
	v_pk_fma_f32 v[214:215], v[86:87], v[216:217], v[214:215]
	v_cvt_pk_bf16_f32 v216, v210, v211
	v_mul_f32_e32 v180, 0xbfb8aa3b, v215
	v_exp_f32_e32 v180, v180
	v_mul_f32_e32 v199, 0xbfb8aa3b, v214
	v_exp_f32_e32 v199, v199
	v_mov_b32_dpp v246, v110 row_shl:15 row_mask:0xf bank_mask:0xf bound_ctrl:1
	v_add_f32_e32 v180, 1.0, v180
	v_rcp_f32_e32 v211, v180
	v_add_f32_e32 v180, 1.0, v199
	v_rcp_f32_e32 v210, v180
	v_mov_b32_dpp v245, v95 row_shr:1 row_mask:0xf bank_mask:0xf bound_ctrl:1
	v_mov_b32_dpp v247, v111 row_shl:15 row_mask:0xf bank_mask:0xf bound_ctrl:1
	v_mov_b32_dpp v248, v94 row_shr:2 row_mask:0xf bank_mask:0xf bound_ctrl:1
	v_mov_b32_dpp v202, v110 row_shl:14 row_mask:0xf bank_mask:0xf bound_ctrl:1
	v_mov_b32_dpp v249, v95 row_shr:2 row_mask:0xf bank_mask:0xf bound_ctrl:1
	v_mov_b32_dpp v203, v111 row_shl:14 row_mask:0xf bank_mask:0xf bound_ctrl:1
	v_pk_fma_f32 v[222:223], v[122:123], v[94:95], v[74:75]
	v_pk_add_f32 v[218:219], v[244:245], v[246:247]
	v_pk_add_f32 v[202:203], v[248:249], v[202:203]
	v_pk_fma_f32 v[218:219], v[118:119], v[218:219], v[222:223]
	v_pk_mul_f32 v[210:211], v[214:215], v[210:211]
	v_pk_fma_f32 v[202:203], v[106:107], v[202:203], v[218:219]
	v_mov_b32_dpp v214, v80 row_shr:2 row_mask:0xf bank_mask:0xf bound_ctrl:1
	v_pk_mul_f32 v[202:203], v[202:203], v[210:211]
	v_lshlrev_b64 v[210:211], 1, v[212:213]
	v_cvt_pk_bf16_f32 v217, v202, v203
	v_lshl_add_u64 v[164:165], v[164:165], 0, v[210:211]
	global_store_dwordx2 v[164:165], v[216:217], off
	v_mov_b32_dpp v202, v96 row_shl:15 row_mask:0xf bank_mask:0xf bound_ctrl:1
	v_mov_b32_dpp v164, v80 row_shr:1 row_mask:0xf bank_mask:0xf bound_ctrl:1
	v_mov_b32_dpp v165, v81 row_shr:1 row_mask:0xf bank_mask:0xf bound_ctrl:1
	v_mov_b32_dpp v203, v97 row_shl:15 row_mask:0xf bank_mask:0xf bound_ctrl:1
	v_mov_b32_dpp v216, v96 row_shl:14 row_mask:0xf bank_mask:0xf bound_ctrl:1
	v_mov_b32_dpp v215, v81 row_shr:2 row_mask:0xf bank_mask:0xf bound_ctrl:1
	v_mov_b32_dpp v217, v97 row_shl:14 row_mask:0xf bank_mask:0xf bound_ctrl:1
	v_pk_add_f32 v[164:165], v[164:165], v[202:203]
	v_pk_fma_f32 v[202:203], v[100:101], v[80:81], v[124:125]
	v_pk_add_f32 v[214:215], v[214:215], v[216:217]
	v_pk_fma_f32 v[164:165], v[88:89], v[164:165], v[202:203]
	v_mov_b32_dpp v218, v76 row_shr:1 row_mask:0xf bank_mask:0xf bound_ctrl:1
	v_pk_fma_f32 v[164:165], v[84:85], v[214:215], v[164:165]
	v_mov_b32_dpp v220, v92 row_shl:15 row_mask:0xf bank_mask:0xf bound_ctrl:1
	v_mul_f32_e32 v180, 0xbfb8aa3b, v165
	v_exp_f32_e32 v180, v180
	v_mov_b32_dpp v222, v76 row_shr:2 row_mask:0xf bank_mask:0xf bound_ctrl:1
; DI float silu_fast(float x) { return x * __builtin_amdgcn_rcpf(1.f + __expf(-x)); }
; template <int CTRL> DI float dppf(float v) { return __builtin_bit_cast(float, __builtin_amdgcn_update_dpp(0, __builtin_bit_cast(int, v), CTRL, 0xf, 0xf, true)); }
; DI void Epi::fused(const f32x4 (&acc)[2][2][4][2], int pm, int pn, int wr, int wc, int fr, int fq) const {
;     ...
;             for (int m = 0; m < 4; ++m) {
;                 const f32x4 ca = acc[ai][bj][m][0], cb = acc[ai][bj][m][1];
;                 const int row = pm * 256 + ai * 128 + wr * 64 + m * 16 + fr;
;                 float o[4];
; #pragma unroll
;                 for (int e = 0; e < 4; ++e) {
;                     const float a1 = dppf<0x111>(ca[e]) + dppf<0x10F>(pa[e]), a2 = dppf<0x112>(ca[e]) + dppf<0x10E>(pa[e]);
;                     const float b1 = dppf<0x111>(cb[e]) + dppf<0x10F>(pb[e]), b2 = dppf<0x112>(cb[e]) + dppf<0x10E>(pb[e]);
;                     const float ya = fmaf(wa0[e], a2, fmaf(wa1[e], a1, fmaf(wa2[e], ca[e], ba[e])));
;                     const float yb = fmaf(wb0[e], b2, fmaf(wb1[e], b1, fmaf(wb2[e], cb[e], bb[e])));
;                     o[e] = silu_fast(ya) * yb; }
;                 if (m > 0 || fr >= 2) { u32x2 w; w.x = pk2(o[0], o[1]); w.y = pk2(o[2], o[3]); *(u32x2*)(E.d0 + (size_t)row * FFH + j0) = w; }
;                 if ((m == 0 && fr < 2) || (m == 3 && fr >= 14)) { float* hb = E.f0 + ((size_t)(row >> 6) * 4 + (m == 0 ? fr : fr - 12)) * FF2 + ncol; *(f32x4*)hb = ca; *(f32x4*)(hb + 4) = cb; }
	v_mov_b32_dpp v224, v92 row_shl:14 row_mask:0xf bank_mask:0xf bound_ctrl:1
	v_mov_b32_dpp v219, v77 row_shr:1 row_mask:0xf bank_mask:0xf bound_ctrl:1
	v_add_f32_e32 v180, 1.0, v180
	v_rcp_f32_e32 v215, v180
	v_mul_f32_e32 v180, 0xbfb8aa3b, v164
	v_exp_f32_e32 v180, v180
	v_mov_b32_dpp v221, v93 row_shl:15 row_mask:0xf bank_mask:0xf bound_ctrl:1
	v_mov_b32_dpp v223, v77 row_shr:2 row_mask:0xf bank_mask:0xf bound_ctrl:1
	v_mov_b32_dpp v225, v93 row_shl:14 row_mask:0xf bank_mask:0xf bound_ctrl:1
	v_add_f32_e32 v180, 1.0, v180
	v_rcp_f32_e32 v214, v180
	v_pk_add_f32 v[216:217], v[222:223], v[224:225]
	v_pk_add_f32 v[218:219], v[218:219], v[220:221]
	v_pk_fma_f32 v[222:223], v[120:121], v[76:77], v[72:73]
	v_mov_b32_dpp v226, v82 row_shr:1 row_mask:0xf bank_mask:0xf bound_ctrl:1
	v_pk_fma_f32 v[218:219], v[116:117], v[218:219], v[222:223]
	v_mov_b32_dpp v228, v98 row_shl:15 row_mask:0xf bank_mask:0xf bound_ctrl:1
	v_mov_b32_dpp v227, v83 row_shr:1 row_mask:0xf bank_mask:0xf bound_ctrl:1
	v_mov_b32_dpp v229, v99 row_shl:15 row_mask:0xf bank_mask:0xf bound_ctrl:1
	v_pk_fma_f32 v[216:217], v[104:105], v[216:217], v[218:219]
	v_pk_mul_f32 v[164:165], v[164:165], v[214:215]
	v_mov_b32_dpp v232, v82 row_shr:2 row_mask:0xf bank_mask:0xf bound_ctrl:1
	v_mov_b32_dpp v238, v98 row_shl:14 row_mask:0xf bank_mask:0xf bound_ctrl:1
	v_mov_b32_dpp v233, v83 row_shr:2 row_mask:0xf bank_mask:0xf bound_ctrl:1
	v_mov_b32_dpp v239, v99 row_shl:14 row_mask:0xf bank_mask:0xf bound_ctrl:1
	v_pk_fma_f32 v[202:203], v[102:103], v[82:83], v[126:127]
	v_pk_mul_f32 v[164:165], v[216:217], v[164:165]
	v_pk_add_f32 v[216:217], v[226:227], v[228:229]
	v_pk_add_f32 v[214:215], v[232:233], v[238:239]
	v_pk_fma_f32 v[202:203], v[90:91], v[216:217], v[202:203]
	v_cvt_pk_bf16_f32 v164, v164, v165
	v_pk_fma_f32 v[202:203], v[86:87], v[214:215], v[202:203]
	v_mov_b32_dpp v240, v78 row_shr:1 row_mask:0xf bank_mask:0xf bound_ctrl:1
	v_mul_f32_e32 v180, 0xbfb8aa3b, v203
	v_mul_f32_e32 v165, 0xbfb8aa3b, v202
	v_exp_f32_e32 v180, v180
	v_exp_f32_e32 v165, v165
	v_mov_b32_dpp v244, v94 row_shl:15 row_mask:0xf bank_mask:0xf bound_ctrl:1
	v_mov_b32_dpp v241, v79 row_shr:1 row_mask:0xf bank_mask:0xf bound_ctrl:1
	v_add_f32_e32 v180, 1.0, v180
	v_add_f32_e32 v165, 1.0, v165
	v_rcp_f32_e32 v215, v180
	v_rcp_f32_e32 v214, v165
	v_mov_b32_dpp v245, v95 row_shl:15 row_mask:0xf bank_mask:0xf bound_ctrl:1
	v_mov_b32_dpp v246, v78 row_shr:2 row_mask:0xf bank_mask:0xf bound_ctrl:1
	v_mov_b32_dpp v248, v94 row_shl:14 row_mask:0xf bank_mask:0xf bound_ctrl:1
	v_mov_b32_dpp v247, v79 row_shr:2 row_mask:0xf bank_mask:0xf bound_ctrl:1
	v_mov_b32_dpp v249, v95 row_shl:14 row_mask:0xf bank_mask:0xf bound_ctrl:1
	v_pk_fma_f32 v[220:221], v[122:123], v[78:79], v[74:75]
	v_pk_add_f32 v[218:219], v[240:241], v[244:245]
	v_pk_add_f32 v[216:217], v[246:247], v[248:249]
	v_pk_fma_f32 v[218:219], v[118:119], v[218:219], v[220:221]
	v_pk_mul_f32 v[202:203], v[202:203], v[214:215]
	v_pk_fma_f32 v[216:217], v[106:107], v[216:217], v[218:219]
	v_lshl_add_u64 v[166:167], v[166:167], 0, v[210:211]
	v_pk_mul_f32 v[202:203], v[216:217], v[202:203]
	v_mov_b32_dpp v214, v80 row_shl:14 row_mask:0xf bank_mask:0xf bound_ctrl:1
	v_cvt_pk_bf16_f32 v165, v202, v203
	global_store_dwordx2 v[166:167], v[164:165], off
	v_mov_b32_dpp v164, v68 row_shr:1 row_mask:0xf bank_mask:0xf bound_ctrl:1
	v_mov_b32_dpp v166, v80 row_shl:15 row_mask:0xf bank_mask:0xf bound_ctrl:1
	v_mov_b32_dpp v165, v69 row_shr:1 row_mask:0xf bank_mask:0xf bound_ctrl:1
	v_mov_b32_dpp v167, v81 row_shl:15 row_mask:0xf bank_mask:0xf bound_ctrl:1
	v_mov_b32_dpp v202, v68 row_shr:2 row_mask:0xf bank_mask:0xf bound_ctrl:1
	v_mov_b32_dpp v203, v69 row_shr:2 row_mask:0xf bank_mask:0xf bound_ctrl:1
	v_mov_b32_dpp v215, v81 row_shl:14 row_mask:0xf bank_mask:0xf bound_ctrl:1
	v_pk_add_f32 v[164:165], v[164:165], v[166:167]
	v_pk_fma_f32 v[166:167], v[100:101], v[68:69], v[124:125]
	v_pk_add_f32 v[202:203], v[202:203], v[214:215]
	v_pk_fma_f32 v[164:165], v[88:89], v[164:165], v[166:167]
	v_mov_b32_dpp v216, v64 row_shr:1 row_mask:0xf bank_mask:0xf bound_ctrl:1
	v_pk_fma_f32 v[164:165], v[84:85], v[202:203], v[164:165]
	v_mov_b32_dpp v218, v76 row_shl:15 row_mask:0xf bank_mask:0xf bound_ctrl:1
	v_mul_f32_e32 v166, 0xbfb8aa3b, v165
	v_exp_f32_e32 v180, v166
	v_mov_b32_dpp v220, v64 row_shr:2 row_mask:0xf bank_mask:0xf bound_ctrl:1
	v_mov_b32_dpp v222, v76 row_shl:14 row_mask:0xf bank_mask:0xf bound_ctrl:1
	v_mov_b32_dpp v217, v65 row_shr:1 row_mask:0xf bank_mask:0xf bound_ctrl:1
	v_add_f32_e32 v180, 1.0, v180
	v_rcp_f32_e32 v203, v180
	v_mul_f32_e32 v180, 0xbfb8aa3b, v164
	v_exp_f32_e32 v180, v180
	v_mov_b32_dpp v219, v77 row_shl:15 row_mask:0xf bank_mask:0xf bound_ctrl:1
	v_mov_b32_dpp v221, v65 row_shr:2 row_mask:0xf bank_mask:0xf bound_ctrl:1
	v_mov_b32_dpp v223, v77 row_shl:14 row_mask:0xf bank_mask:0xf bound_ctrl:1
	v_add_f32_e32 v180, 1.0, v180
	v_rcp_f32_e32 v202, v180
	v_pk_add_f32 v[214:215], v[220:221], v[222:223]
	v_pk_add_f32 v[216:217], v[216:217], v[218:219]
	v_pk_fma_f32 v[220:221], v[120:121], v[64:65], v[72:73]
	v_mov_b32_dpp v224, v70 row_shr:1 row_mask:0xf bank_mask:0xf bound_ctrl:1
	v_pk_fma_f32 v[216:217], v[116:117], v[216:217], v[220:221]
	v_mov_b32_dpp v226, v82 row_shl:15 row_mask:0xf bank_mask:0xf bound_ctrl:1
	v_mov_b32_dpp v225, v71 row_shr:1 row_mask:0xf bank_mask:0xf bound_ctrl:1
	v_mov_b32_dpp v227, v83 row_shl:15 row_mask:0xf bank_mask:0xf bound_ctrl:1
	v_pk_fma_f32 v[214:215], v[104:105], v[214:215], v[216:217]
	v_pk_mul_f32 v[164:165], v[164:165], v[202:203]
	v_mov_b32_dpp v228, v70 row_shr:2 row_mask:0xf bank_mask:0xf bound_ctrl:1
; DI float silu_fast(float x) { return x * __builtin_amdgcn_rcpf(1.f + __expf(-x)); }
; template <int CTRL> DI float dppf(float v) { return __builtin_bit_cast(float, __builtin_amdgcn_update_dpp(0, __builtin_bit_cast(int, v), CTRL, 0xf, 0xf, true)); }
; DI void Epi::fused(const f32x4 (&acc)[2][2][4][2], int pm, int pn, int wr, int wc, int fr, int fq) const {
;     ...
;             for (int m = 0; m < 4; ++m) {
;                 const f32x4 ca = acc[ai][bj][m][0], cb = acc[ai][bj][m][1];
;                 const int row = pm * 256 + ai * 128 + wr * 64 + m * 16 + fr;
;                 float o[4];
; #pragma unroll
;                 for (int e = 0; e < 4; ++e) {
;                     const float a1 = dppf<0x111>(ca[e]) + dppf<0x10F>(pa[e]), a2 = dppf<0x112>(ca[e]) + dppf<0x10E>(pa[e]);
;                     const float b1 = dppf<0x111>(cb[e]) + dppf<0x10F>(pb[e]), b2 = dppf<0x112>(cb[e]) + dppf<0x10E>(pb[e]);
;                     const float ya = fmaf(wa0[e], a2, fmaf(wa1[e], a1, fmaf(wa2[e], ca[e], ba[e])));
;                     const float yb = fmaf(wb0[e], b2, fmaf(wb1[e], b1, fmaf(wb2[e], cb[e], bb[e])));
;                     o[e] = silu_fast(ya) * yb; }
;                 if (m > 0 || fr >= 2) { u32x2 w; w.x = pk2(o[0], o[1]); w.y = pk2(o[2], o[3]); *(u32x2*)(E.d0 + (size_t)row * FFH + j0) = w; }
;                 if ((m == 0 && fr < 2) || (m == 3 && fr >= 14)) { float* hb = E.f0 + ((size_t)(row >> 6) * 4 + (m == 0 ? fr : fr - 12)) * FF2 + ncol; *(f32x4*)hb = ca; *(f32x4*)(hb + 4) = cb; }
	v_mov_b32_dpp v232, v82 row_shl:14 row_mask:0xf bank_mask:0xf bound_ctrl:1
	v_mov_b32_dpp v229, v71 row_shr:2 row_mask:0xf bank_mask:0xf bound_ctrl:1
	v_mov_b32_dpp v233, v83 row_shl:14 row_mask:0xf bank_mask:0xf bound_ctrl:1
	v_pk_fma_f32 v[166:167], v[102:103], v[70:71], v[126:127]
	v_pk_mul_f32 v[164:165], v[214:215], v[164:165]
	v_pk_add_f32 v[214:215], v[224:225], v[226:227]
	v_pk_add_f32 v[202:203], v[228:229], v[232:233]
	v_pk_fma_f32 v[166:167], v[90:91], v[214:215], v[166:167]
	v_cvt_pk_bf16_f32 v164, v164, v165
	v_pk_fma_f32 v[166:167], v[86:87], v[202:203], v[166:167]
	v_mov_b32_dpp v238, v66 row_shr:1 row_mask:0xf bank_mask:0xf bound_ctrl:1
	v_mul_f32_e32 v180, 0xbfb8aa3b, v167
	v_mul_f32_e32 v165, 0xbfb8aa3b, v166
	v_exp_f32_e32 v180, v180
	v_exp_f32_e32 v165, v165
	v_mov_b32_dpp v240, v78 row_shl:15 row_mask:0xf bank_mask:0xf bound_ctrl:1
	v_mov_b32_dpp v239, v67 row_shr:1 row_mask:0xf bank_mask:0xf bound_ctrl:1
	v_add_f32_e32 v180, 1.0, v180
	v_add_f32_e32 v165, 1.0, v165
	v_rcp_f32_e32 v203, v180
	v_rcp_f32_e32 v202, v165
	v_mov_b32_dpp v241, v79 row_shl:15 row_mask:0xf bank_mask:0xf bound_ctrl:1
	v_mov_b32_dpp v244, v66 row_shr:2 row_mask:0xf bank_mask:0xf bound_ctrl:1
	v_mov_b32_dpp v246, v78 row_shl:14 row_mask:0xf bank_mask:0xf bound_ctrl:1
	v_mov_b32_dpp v245, v67 row_shr:2 row_mask:0xf bank_mask:0xf bound_ctrl:1
	v_mov_b32_dpp v247, v79 row_shl:14 row_mask:0xf bank_mask:0xf bound_ctrl:1
	v_pk_fma_f32 v[218:219], v[122:123], v[66:67], v[74:75]
	v_pk_add_f32 v[216:217], v[238:239], v[240:241]
	v_pk_add_f32 v[214:215], v[244:245], v[246:247]
	v_pk_fma_f32 v[216:217], v[118:119], v[216:217], v[218:219]
	v_pk_mul_f32 v[166:167], v[166:167], v[202:203]
	v_pk_fma_f32 v[214:215], v[106:107], v[214:215], v[216:217]
	s_nop 0
	v_pk_mul_f32 v[166:167], v[214:215], v[166:167]
	s_nop 0
	v_cvt_pk_bf16_f32 v165, v166, v167
	v_lshl_add_u64 v[166:167], v[168:169], 0, v[210:211]
	global_store_dwordx2 v[166:167], v[164:165], off
	s_and_saveexec_b64 s[76:77], s[42:43]
	s_cbranch_execz .LBB0_678
	v_mov_b64_e32 v[164:165], s[8:9]
	s_movk_i32 s71, 0x5800
	v_mad_u64_u32 v[164:165], s[78:79], v162, s71, v[164:165]
	v_mad_i32_i24 v165, v163, s71, v165
	v_lshl_add_u64 v[162:163], v[160:161], 2, v[164:165]
	global_store_dwordx4 v[162:163], v[68:71], off offset:512
	global_store_dwordx4 v[162:163], v[64:67], off offset:528
.LBB0_678:
	s_or_b64 exec, exec, s[76:77]
	v_mov_b32_dpp v222, v48 row_shr:1 row_mask:0xf bank_mask:0xf bound_ctrl:1
	v_mov_b32_dpp v162, v181 row_shl:15 row_mask:0xf bank_mask:0xf bound_ctrl:1
	v_mov_b32_dpp v224, v48 row_shr:2 row_mask:0xf bank_mask:0xf bound_ctrl:1
	v_mov_b32_dpp v164, v181 row_shl:14 row_mask:0xf bank_mask:0xf bound_ctrl:1
	v_mov_b32_dpp v218, v44 row_shr:1 row_mask:0xf bank_mask:0xf bound_ctrl:1
	v_mov_b32_dpp v220, v44 row_shr:2 row_mask:0xf bank_mask:0xf bound_ctrl:1
	v_mov_b32_dpp v223, v49 row_shr:1 row_mask:0xf bank_mask:0xf bound_ctrl:1
	v_mov_b32_dpp v225, v49 row_shr:2 row_mask:0xf bank_mask:0xf bound_ctrl:1
	v_mov_b32_dpp v219, v45 row_shr:1 row_mask:0xf bank_mask:0xf bound_ctrl:1
	v_mov_b32_dpp v221, v45 row_shr:2 row_mask:0xf bank_mask:0xf bound_ctrl:1
	v_mov_b32_dpp v214, v50 row_shr:1 row_mask:0xf bank_mask:0xf bound_ctrl:1
	v_mov_b32_dpp v216, v50 row_shr:2 row_mask:0xf bank_mask:0xf bound_ctrl:1
	v_mov_b32_dpp v166, v46 row_shr:1 row_mask:0xf bank_mask:0xf bound_ctrl:1
	v_mov_b32_dpp v168, v46 row_shr:2 row_mask:0xf bank_mask:0xf bound_ctrl:1
	v_mov_b32_dpp v215, v51 row_shr:1 row_mask:0xf bank_mask:0xf bound_ctrl:1
	v_mov_b32_dpp v217, v51 row_shr:2 row_mask:0xf bank_mask:0xf bound_ctrl:1
	v_mov_b32_dpp v167, v47 row_shr:1 row_mask:0xf bank_mask:0xf bound_ctrl:1
	v_mov_b32_dpp v169, v47 row_shr:2 row_mask:0xf bank_mask:0xf bound_ctrl:1
	s_and_saveexec_b64 s[76:77], s[38:39]
	s_cbranch_execz .LBB0_680
	v_pk_fma_f32 v[228:229], v[100:101], v[48:49], v[124:125]
	v_pk_add_f32 v[222:223], v[162:163], v[222:223] op_sel_hi:[0,1]
	v_pk_add_f32 v[224:225], v[164:165], v[224:225] op_sel_hi:[0,1]
	v_pk_fma_f32 v[222:223], v[88:89], v[222:223], v[228:229]
	v_pk_fma_f32 v[202:203], v[122:123], v[46:47], v[74:75]
	v_pk_fma_f32 v[222:223], v[84:85], v[224:225], v[222:223]
	v_pk_fma_f32 v[224:225], v[102:103], v[50:51], v[126:127]
	v_mul_f32_e32 v163, 0xbfb8aa3b, v223
	v_exp_f32_e32 v163, v163
	v_mul_f32_e32 v165, 0xbfb8aa3b, v222
	v_exp_f32_e32 v165, v165
	v_pk_fma_f32 v[226:227], v[120:121], v[44:45], v[72:73]
	v_add_f32_e32 v163, 1.0, v163
	v_rcp_f32_e32 v229, v163
	v_add_f32_e32 v163, 1.0, v165
	v_pk_add_f32 v[214:215], v[162:163], v[214:215] op_sel_hi:[0,1]
	v_pk_add_f32 v[216:217], v[164:165], v[216:217] op_sel_hi:[0,1]
	v_pk_fma_f32 v[214:215], v[90:91], v[214:215], v[224:225]
	v_rcp_f32_e32 v228, v163
	v_pk_fma_f32 v[214:215], v[86:87], v[216:217], v[214:215]
	v_pk_add_f32 v[218:219], v[162:163], v[218:219] op_sel_hi:[0,1]
	v_mul_f32_e32 v163, 0xbfb8aa3b, v215
	v_exp_f32_e32 v163, v163
	v_pk_add_f32 v[220:221], v[164:165], v[220:221] op_sel_hi:[0,1]
	v_mul_f32_e32 v165, 0xbfb8aa3b, v214
	v_exp_f32_e32 v180, v165
	v_add_f32_e32 v163, 1.0, v163
	v_rcp_f32_e32 v165, v163
	v_pk_fma_f32 v[218:219], v[116:117], v[218:219], v[226:227]
	v_add_f32_e32 v163, 1.0, v180
	v_pk_fma_f32 v[218:219], v[104:105], v[220:221], v[218:219]
	v_pk_add_f32 v[168:169], v[164:165], v[168:169] op_sel_hi:[0,1]
	v_rcp_f32_e32 v164, v163
	v_pk_add_f32 v[162:163], v[162:163], v[166:167] op_sel_hi:[0,1]
	v_pk_fma_f32 v[162:163], v[118:119], v[162:163], v[202:203]
	v_pk_mul_f32 v[220:221], v[222:223], v[228:229]
	v_pk_fma_f32 v[162:163], v[106:107], v[168:169], v[162:163]
	v_pk_mul_f32 v[164:165], v[214:215], v[164:165]
	s_movk_i32 s71, 0x1600
	v_pk_mul_f32 v[162:163], v[162:163], v[164:165]
	v_pk_mul_f32 v[218:219], v[218:219], v[220:221]
	v_cvt_pk_bf16_f32 v217, v162, v163
	v_mov_b64_e32 v[162:163], s[12:13]
	v_mad_i64_i32 v[162:163], s[78:79], v201, s71, v[162:163]
	v_cvt_pk_bf16_f32 v216, v218, v219
	v_lshl_add_u64 v[162:163], v[212:213], 1, v[162:163]
	global_store_dwordx2 v[162:163], v[216:217], off

; DI float silu_fast(float x) { return x * __builtin_amdgcn_rcpf(1.f + __expf(-x)); }
; template <int CTRL> DI float dppf(float v) { return __builtin_bit_cast(float, __builtin_amdgcn_update_dpp(0, __builtin_bit_cast(int, v), CTRL, 0xf, 0xf, true)); }
; DI void Epi::fused(const f32x4 (&acc)[2][2][4][2], int pm, int pn, int wr, int wc, int fr, int fq) const {
;     ...
;             for (int m = 0; m < 4; ++m) {
;                 const f32x4 ca = acc[ai][bj][m][0], cb = acc[ai][bj][m][1];
;                 const int row = pm * 256 + ai * 128 + wr * 64 + m * 16 + fr;
;                 float o[4];
; #pragma unroll
;                 for (int e = 0; e < 4; ++e) {
;                     const float a1 = dppf<0x111>(ca[e]) + dppf<0x10F>(pa[e]), a2 = dppf<0x112>(ca[e]) + dppf<0x10E>(pa[e]);
;                     const float b1 = dppf<0x111>(cb[e]) + dppf<0x10F>(pb[e]), b2 = dppf<0x112>(cb[e]) + dppf<0x10E>(pb[e]);
;                     const float ya = fmaf(wa0[e], a2, fmaf(wa1[e], a1, fmaf(wa2[e], ca[e], ba[e])));
;                     const float yb = fmaf(wb0[e], b2, fmaf(wb1[e], b1, fmaf(wb2[e], cb[e], bb[e])));
;                     o[e] = silu_fast(ya) * yb; }
;                 if (m > 0 || fr >= 2) { u32x2 w; w.x = pk2(o[0], o[1]); w.y = pk2(o[2], o[3]); *(u32x2*)(E.d0 + (size_t)row * FFH + j0) = w; }
;                 if ((m == 0 && fr < 2) || (m == 3 && fr >= 14)) { float* hb = E.f0 + ((size_t)(row >> 6) * 4 + (m == 0 ? fr : fr - 12)) * FF2 + ncol; *(f32x4*)hb = ca; *(f32x4*)(hb + 4) = cb; }
.LBB0_682:
	s_or_b64 exec, exec, s[76:77]
	v_mov_b32_dpp v162, v24 row_shr:1 row_mask:0xf bank_mask:0xf bound_ctrl:1
	v_mov_b32_dpp v164, v48 row_shl:15 row_mask:0xf bank_mask:0xf bound_ctrl:1
	v_mov_b32_dpp v163, v25 row_shr:1 row_mask:0xf bank_mask:0xf bound_ctrl:1
	v_mov_b32_dpp v165, v49 row_shl:15 row_mask:0xf bank_mask:0xf bound_ctrl:1
	v_mov_b32_dpp v166, v24 row_shr:2 row_mask:0xf bank_mask:0xf bound_ctrl:1
	v_mov_b32_dpp v168, v48 row_shl:14 row_mask:0xf bank_mask:0xf bound_ctrl:1
	v_mov_b32_dpp v167, v25 row_shr:2 row_mask:0xf bank_mask:0xf bound_ctrl:1
	v_mov_b32_dpp v169, v49 row_shl:14 row_mask:0xf bank_mask:0xf bound_ctrl:1
	v_pk_add_f32 v[162:163], v[162:163], v[164:165]
	v_pk_fma_f32 v[164:165], v[100:101], v[24:25], v[124:125]
	v_pk_add_f32 v[166:167], v[166:167], v[168:169]
	v_pk_fma_f32 v[162:163], v[88:89], v[162:163], v[164:165]
	v_mov_b32_dpp v202, v20 row_shr:1 row_mask:0xf bank_mask:0xf bound_ctrl:1
	v_pk_fma_f32 v[162:163], v[84:85], v[166:167], v[162:163]
	v_mov_b32_dpp v212, v44 row_shl:15 row_mask:0xf bank_mask:0xf bound_ctrl:1
	v_mul_f32_e32 v164, 0xbfb8aa3b, v163
	v_exp_f32_e32 v166, v164
	v_mov_b32_dpp v214, v20 row_shr:2 row_mask:0xf bank_mask:0xf bound_ctrl:1
	v_mov_b32_dpp v216, v44 row_shl:14 row_mask:0xf bank_mask:0xf bound_ctrl:1
	v_mov_b32_dpp v203, v21 row_shr:1 row_mask:0xf bank_mask:0xf bound_ctrl:1
	v_add_f32_e32 v166, 1.0, v166
	v_rcp_f32_e32 v167, v166
	v_mul_f32_e32 v166, 0xbfb8aa3b, v162
	v_exp_f32_e32 v166, v166
	v_mov_b32_dpp v213, v45 row_shl:15 row_mask:0xf bank_mask:0xf bound_ctrl:1
	v_mov_b32_dpp v215, v21 row_shr:2 row_mask:0xf bank_mask:0xf bound_ctrl:1
	v_mov_b32_dpp v217, v45 row_shl:14 row_mask:0xf bank_mask:0xf bound_ctrl:1
	v_add_f32_e32 v166, 1.0, v166
	v_rcp_f32_e32 v166, v166
	v_pk_add_f32 v[168:169], v[214:215], v[216:217]
	v_pk_add_f32 v[202:203], v[202:203], v[212:213]
	v_pk_fma_f32 v[214:215], v[120:121], v[20:21], v[72:73]
	v_mov_b32_dpp v218, v26 row_shr:1 row_mask:0xf bank_mask:0xf bound_ctrl:1
	v_pk_fma_f32 v[202:203], v[116:117], v[202:203], v[214:215]
	v_mov_b32_dpp v220, v50 row_shl:15 row_mask:0xf bank_mask:0xf bound_ctrl:1
	v_mov_b32_dpp v219, v27 row_shr:1 row_mask:0xf bank_mask:0xf bound_ctrl:1
	v_mov_b32_dpp v221, v51 row_shl:15 row_mask:0xf bank_mask:0xf bound_ctrl:1
	v_pk_fma_f32 v[168:169], v[104:105], v[168:169], v[202:203]
	v_pk_mul_f32 v[162:163], v[162:163], v[166:167]
	v_mov_b32_dpp v222, v26 row_shr:2 row_mask:0xf bank_mask:0xf bound_ctrl:1
	v_mov_b32_dpp v224, v50 row_shl:14 row_mask:0xf bank_mask:0xf bound_ctrl:1
	v_mov_b32_dpp v223, v27 row_shr:2 row_mask:0xf bank_mask:0xf bound_ctrl:1
	v_mov_b32_dpp v225, v51 row_shl:14 row_mask:0xf bank_mask:0xf bound_ctrl:1
	v_pk_fma_f32 v[164:165], v[102:103], v[26:27], v[126:127]
	v_pk_mul_f32 v[162:163], v[168:169], v[162:163]
	v_pk_add_f32 v[168:169], v[218:219], v[220:221]
	v_pk_add_f32 v[166:167], v[222:223], v[224:225]
	v_pk_fma_f32 v[164:165], v[90:91], v[168:169], v[164:165]
	v_cvt_pk_bf16_f32 v162, v162, v163
	v_pk_fma_f32 v[164:165], v[86:87], v[166:167], v[164:165]
	v_mov_b32_dpp v226, v22 row_shr:1 row_mask:0xf bank_mask:0xf bound_ctrl:1
	v_mul_f32_e32 v166, 0xbfb8aa3b, v165
	v_mul_f32_e32 v163, 0xbfb8aa3b, v164
	v_exp_f32_e32 v166, v166
	v_exp_f32_e32 v163, v163
	v_mov_b32_dpp v228, v46 row_shl:15 row_mask:0xf bank_mask:0xf bound_ctrl:1
	v_mov_b32_dpp v227, v23 row_shr:1 row_mask:0xf bank_mask:0xf bound_ctrl:1
	v_add_f32_e32 v166, 1.0, v166
	v_add_f32_e32 v163, 1.0, v163
	v_rcp_f32_e32 v167, v166
	v_rcp_f32_e32 v166, v163
	v_mov_b32_dpp v229, v47 row_shl:15 row_mask:0xf bank_mask:0xf bound_ctrl:1
	v_mov_b32_dpp v232, v22 row_shr:2 row_mask:0xf bank_mask:0xf bound_ctrl:1
	v_mov_b32_dpp v238, v46 row_shl:14 row_mask:0xf bank_mask:0xf bound_ctrl:1
	v_mov_b32_dpp v233, v23 row_shr:2 row_mask:0xf bank_mask:0xf bound_ctrl:1
	v_mov_b32_dpp v239, v47 row_shl:14 row_mask:0xf bank_mask:0xf bound_ctrl:1
	v_pk_fma_f32 v[212:213], v[122:123], v[22:23], v[74:75]
	v_pk_add_f32 v[202:203], v[226:227], v[228:229]
	v_pk_add_f32 v[168:169], v[232:233], v[238:239]
	v_pk_fma_f32 v[202:203], v[118:119], v[202:203], v[212:213]
	v_pk_mul_f32 v[164:165], v[164:165], v[166:167]
	v_pk_fma_f32 v[168:169], v[106:107], v[168:169], v[202:203]
	v_mov_b32_dpp v166, v28 row_shr:2 row_mask:0xf bank_mask:0xf bound_ctrl:1
	v_pk_mul_f32 v[164:165], v[168:169], v[164:165]
	v_mov_b32_dpp v168, v24 row_shl:14 row_mask:0xf bank_mask:0xf bound_ctrl:1
	v_cvt_pk_bf16_f32 v163, v164, v165
	v_lshl_add_u64 v[164:165], v[172:173], 0, v[210:211]
	global_store_dwordx2 v[164:165], v[162:163], off
	v_mov_b32_dpp v162, v28 row_shr:1 row_mask:0xf bank_mask:0xf bound_ctrl:1
	v_mov_b32_dpp v164, v24 row_shl:15 row_mask:0xf bank_mask:0xf bound_ctrl:1
	v_mov_b32_dpp v163, v29 row_shr:1 row_mask:0xf bank_mask:0xf bound_ctrl:1
	v_mov_b32_dpp v165, v25 row_shl:15 row_mask:0xf bank_mask:0xf bound_ctrl:1
	v_mov_b32_dpp v167, v29 row_shr:2 row_mask:0xf bank_mask:0xf bound_ctrl:1
	v_mov_b32_dpp v169, v25 row_shl:14 row_mask:0xf bank_mask:0xf bound_ctrl:1
	v_pk_add_f32 v[162:163], v[162:163], v[164:165]
	v_pk_fma_f32 v[164:165], v[100:101], v[28:29], v[124:125]
	v_pk_add_f32 v[166:167], v[166:167], v[168:169]
	v_pk_fma_f32 v[162:163], v[88:89], v[162:163], v[164:165]
	v_mov_b32_dpp v172, v32 row_shr:1 row_mask:0xf bank_mask:0xf bound_ctrl:1
	v_pk_fma_f32 v[162:163], v[84:85], v[166:167], v[162:163]
	v_mov_b32_dpp v202, v20 row_shl:15 row_mask:0xf bank_mask:0xf bound_ctrl:1
	v_mul_f32_e32 v164, 0xbfb8aa3b, v163
	v_exp_f32_e32 v166, v164
	v_mov_b32_dpp v212, v32 row_shr:2 row_mask:0xf bank_mask:0xf bound_ctrl:1
	v_mov_b32_dpp v214, v20 row_shl:14 row_mask:0xf bank_mask:0xf bound_ctrl:1
; DI float silu_fast(float x) { return x * __builtin_amdgcn_rcpf(1.f + __expf(-x)); }
; template <int CTRL> DI float dppf(float v) { return __builtin_bit_cast(float, __builtin_amdgcn_update_dpp(0, __builtin_bit_cast(int, v), CTRL, 0xf, 0xf, true)); }
; DI void Epi::fused(const f32x4 (&acc)[2][2][4][2], int pm, int pn, int wr, int wc, int fr, int fq) const {
;     ...
;             for (int m = 0; m < 4; ++m) {
;                 const f32x4 ca = acc[ai][bj][m][0], cb = acc[ai][bj][m][1];
;                 const int row = pm * 256 + ai * 128 + wr * 64 + m * 16 + fr;
;                 float o[4];
; #pragma unroll
;                 for (int e = 0; e < 4; ++e) {
;                     const float a1 = dppf<0x111>(ca[e]) + dppf<0x10F>(pa[e]), a2 = dppf<0x112>(ca[e]) + dppf<0x10E>(pa[e]);
;                     const float b1 = dppf<0x111>(cb[e]) + dppf<0x10F>(pb[e]), b2 = dppf<0x112>(cb[e]) + dppf<0x10E>(pb[e]);
;                     const float ya = fmaf(wa0[e], a2, fmaf(wa1[e], a1, fmaf(wa2[e], ca[e], ba[e])));
;                     const float yb = fmaf(wb0[e], b2, fmaf(wb1[e], b1, fmaf(wb2[e], cb[e], bb[e])));
;                     o[e] = silu_fast(ya) * yb; }
;                 if (m > 0 || fr >= 2) { u32x2 w; w.x = pk2(o[0], o[1]); w.y = pk2(o[2], o[3]); *(u32x2*)(E.d0 + (size_t)row * FFH + j0) = w; }
;                 if ((m == 0 && fr < 2) || (m == 3 && fr >= 14)) { float* hb = E.f0 + ((size_t)(row >> 6) * 4 + (m == 0 ? fr : fr - 12)) * FF2 + ncol; *(f32x4*)hb = ca; *(f32x4*)(hb + 4) = cb; }
	v_mov_b32_dpp v173, v33 row_shr:1 row_mask:0xf bank_mask:0xf bound_ctrl:1
	v_add_f32_e32 v166, 1.0, v166
	v_rcp_f32_e32 v167, v166
	v_mul_f32_e32 v166, 0xbfb8aa3b, v162
	v_exp_f32_e32 v166, v166
	v_mov_b32_dpp v203, v21 row_shl:15 row_mask:0xf bank_mask:0xf bound_ctrl:1
	v_mov_b32_dpp v213, v33 row_shr:2 row_mask:0xf bank_mask:0xf bound_ctrl:1
	v_mov_b32_dpp v215, v21 row_shl:14 row_mask:0xf bank_mask:0xf bound_ctrl:1
	v_add_f32_e32 v166, 1.0, v166
	v_rcp_f32_e32 v166, v166
	v_pk_add_f32 v[168:169], v[212:213], v[214:215]
	v_pk_add_f32 v[172:173], v[172:173], v[202:203]
	v_pk_fma_f32 v[212:213], v[120:121], v[32:33], v[72:73]
	v_mov_b32_dpp v216, v30 row_shr:1 row_mask:0xf bank_mask:0xf bound_ctrl:1
	v_pk_fma_f32 v[172:173], v[116:117], v[172:173], v[212:213]
	v_mov_b32_dpp v218, v26 row_shl:15 row_mask:0xf bank_mask:0xf bound_ctrl:1
	v_mov_b32_dpp v217, v31 row_shr:1 row_mask:0xf bank_mask:0xf bound_ctrl:1
	v_mov_b32_dpp v219, v27 row_shl:15 row_mask:0xf bank_mask:0xf bound_ctrl:1
	v_pk_fma_f32 v[168:169], v[104:105], v[168:169], v[172:173]
	v_pk_mul_f32 v[162:163], v[162:163], v[166:167]
	v_mov_b32_dpp v220, v30 row_shr:2 row_mask:0xf bank_mask:0xf bound_ctrl:1
	v_mov_b32_dpp v222, v26 row_shl:14 row_mask:0xf bank_mask:0xf bound_ctrl:1
	v_mov_b32_dpp v221, v31 row_shr:2 row_mask:0xf bank_mask:0xf bound_ctrl:1
	v_mov_b32_dpp v223, v27 row_shl:14 row_mask:0xf bank_mask:0xf bound_ctrl:1
	v_pk_fma_f32 v[164:165], v[102:103], v[30:31], v[126:127]
	v_pk_mul_f32 v[162:163], v[168:169], v[162:163]
	v_pk_add_f32 v[168:169], v[216:217], v[218:219]
	v_pk_add_f32 v[166:167], v[220:221], v[222:223]
	v_pk_fma_f32 v[164:165], v[90:91], v[168:169], v[164:165]
	v_cvt_pk_bf16_f32 v162, v162, v163
	v_pk_fma_f32 v[164:165], v[86:87], v[166:167], v[164:165]
	v_mov_b32_dpp v224, v34 row_shr:1 row_mask:0xf bank_mask:0xf bound_ctrl:1
	v_mul_f32_e32 v166, 0xbfb8aa3b, v165
	v_mul_f32_e32 v163, 0xbfb8aa3b, v164
	v_exp_f32_e32 v166, v166
	v_exp_f32_e32 v163, v163
	v_mov_b32_dpp v226, v22 row_shl:15 row_mask:0xf bank_mask:0xf bound_ctrl:1
	v_mov_b32_dpp v225, v35 row_shr:1 row_mask:0xf bank_mask:0xf bound_ctrl:1
	v_add_f32_e32 v166, 1.0, v166
	v_add_f32_e32 v163, 1.0, v163
	v_rcp_f32_e32 v167, v166
	v_rcp_f32_e32 v166, v163
	v_mov_b32_dpp v227, v23 row_shl:15 row_mask:0xf bank_mask:0xf bound_ctrl:1
	v_mov_b32_dpp v228, v34 row_shr:2 row_mask:0xf bank_mask:0xf bound_ctrl:1
	v_mov_b32_dpp v232, v22 row_shl:14 row_mask:0xf bank_mask:0xf bound_ctrl:1
	v_mov_b32_dpp v229, v35 row_shr:2 row_mask:0xf bank_mask:0xf bound_ctrl:1
	v_mov_b32_dpp v233, v23 row_shl:14 row_mask:0xf bank_mask:0xf bound_ctrl:1
	v_pk_fma_f32 v[202:203], v[122:123], v[34:35], v[74:75]
	v_pk_add_f32 v[172:173], v[224:225], v[226:227]
	v_pk_add_f32 v[168:169], v[228:229], v[232:233]
	v_pk_fma_f32 v[172:173], v[118:119], v[172:173], v[202:203]
	v_pk_mul_f32 v[164:165], v[164:165], v[166:167]
	v_pk_fma_f32 v[168:169], v[106:107], v[168:169], v[172:173]
	v_mov_b32_dpp v166, v8 row_shr:2 row_mask:0xf bank_mask:0xf bound_ctrl:1
	v_pk_mul_f32 v[164:165], v[168:169], v[164:165]
	v_mov_b32_dpp v168, v28 row_shl:14 row_mask:0xf bank_mask:0xf bound_ctrl:1
	v_cvt_pk_bf16_f32 v163, v164, v165
	v_lshl_add_u64 v[164:165], v[174:175], 0, v[210:211]
	global_store_dwordx2 v[164:165], v[162:163], off
	v_mov_b32_dpp v162, v8 row_shr:1 row_mask:0xf bank_mask:0xf bound_ctrl:1
	v_mov_b32_dpp v164, v28 row_shl:15 row_mask:0xf bank_mask:0xf bound_ctrl:1
	v_mov_b32_dpp v163, v9 row_shr:1 row_mask:0xf bank_mask:0xf bound_ctrl:1
	v_mov_b32_dpp v165, v29 row_shl:15 row_mask:0xf bank_mask:0xf bound_ctrl:1
	v_mov_b32_dpp v167, v9 row_shr:2 row_mask:0xf bank_mask:0xf bound_ctrl:1
	v_mov_b32_dpp v169, v29 row_shl:14 row_mask:0xf bank_mask:0xf bound_ctrl:1
	v_pk_add_f32 v[162:163], v[162:163], v[164:165]
	v_pk_fma_f32 v[152:153], v[100:101], v[8:9], v[124:125]
	v_pk_add_f32 v[166:167], v[166:167], v[168:169]
	v_pk_fma_f32 v[140:141], v[88:89], v[162:163], v[152:153]
; DI float silu_fast(float x) { return x * __builtin_amdgcn_rcpf(1.f + __expf(-x)); }
; template <int CTRL> DI float dppf(float v) { return __builtin_bit_cast(float, __builtin_amdgcn_update_dpp(0, __builtin_bit_cast(int, v), CTRL, 0xf, 0xf, true)); }
; DI void Epi::fused(const f32x4 (&acc)[2][2][4][2], int pm, int pn, int wr, int wc, int fr, int fq) const {
;     ...
;                     const float a1 = dppf<0x111>(ca[e]) + dppf<0x10F>(pa[e]), a2 = dppf<0x112>(ca[e]) + dppf<0x10E>(pa[e]);
;                     const float b1 = dppf<0x111>(cb[e]) + dppf<0x10F>(pb[e]), b2 = dppf<0x112>(cb[e]) + dppf<0x10E>(pb[e]);
;                     const float ya = fmaf(wa0[e], a2, fmaf(wa1[e], a1, fmaf(wa2[e], ca[e], ba[e])));
;                     const float yb = fmaf(wb0[e], b2, fmaf(wb1[e], b1, fmaf(wb2[e], cb[e], bb[e])));
;                     o[e] = silu_fast(ya) * yb; }
;                 if (m > 0 || fr >= 2) { u32x2 w; w.x = pk2(o[0], o[1]); w.y = pk2(o[2], o[3]); *(u32x2*)(E.d0 + (size_t)row * FFH + j0) = w; }
;                 if ((m == 0 && fr < 2) || (m == 3 && fr >= 14)) { float* hb = E.f0 + ((size_t)(row >> 6) * 4 + (m == 0 ? fr : fr - 12)) * FF2 + ncol; *(f32x4*)hb = ca; *(f32x4*)(hb + 4) = cb; }
	v_pk_fma_f32 v[146:147], v[122:123], v[6:7], v[74:75]
	v_pk_fma_f32 v[136:137], v[84:85], v[166:167], v[140:141]
	v_mov_b32_dpp v172, v4 row_shr:1 row_mask:0xf bank_mask:0xf bound_ctrl:1
	v_mul_f32_e32 v140, 0xbfb8aa3b, v137
	v_exp_f32_e32 v152, v140
	v_mov_b32_dpp v174, v32 row_shl:15 row_mask:0xf bank_mask:0xf bound_ctrl:1
	v_mov_b32_dpp v173, v5 row_shr:1 row_mask:0xf bank_mask:0xf bound_ctrl:1
	v_mov_b32_dpp v175, v33 row_shl:15 row_mask:0xf bank_mask:0xf bound_ctrl:1
	v_add_f32_e32 v152, 1.0, v152
	v_rcp_f32_e32 v153, v152
	v_mul_f32_e32 v152, 0xbfb8aa3b, v136
	v_exp_f32_e32 v152, v152
	v_mov_b32_dpp v202, v4 row_shr:2 row_mask:0xf bank_mask:0xf bound_ctrl:1
	v_mov_b32_dpp v212, v32 row_shl:14 row_mask:0xf bank_mask:0xf bound_ctrl:1
	v_mov_b32_dpp v203, v5 row_shr:2 row_mask:0xf bank_mask:0xf bound_ctrl:1
	v_add_f32_e32 v150, 1.0, v152
	v_rcp_f32_e32 v152, v150
	v_mov_b32_dpp v213, v33 row_shl:14 row_mask:0xf bank_mask:0xf bound_ctrl:1
	v_pk_add_f32 v[156:157], v[172:173], v[174:175]
	v_pk_fma_f32 v[144:145], v[120:121], v[4:5], v[72:73]
	v_mov_b32_dpp v214, v10 row_shr:1 row_mask:0xf bank_mask:0xf bound_ctrl:1
	v_mov_b32_dpp v216, v30 row_shl:15 row_mask:0xf bank_mask:0xf bound_ctrl:1
	v_mov_b32_dpp v215, v11 row_shr:1 row_mask:0xf bank_mask:0xf bound_ctrl:1
	v_mov_b32_dpp v217, v31 row_shl:15 row_mask:0xf bank_mask:0xf bound_ctrl:1
	v_pk_fma_f32 v[140:141], v[102:103], v[10:11], v[126:127]
	v_pk_add_f32 v[154:155], v[202:203], v[212:213]
	v_pk_fma_f32 v[132:133], v[116:117], v[156:157], v[144:145]
	v_mov_b32_dpp v218, v10 row_shr:2 row_mask:0xf bank_mask:0xf bound_ctrl:1
	v_mov_b32_dpp v220, v30 row_shl:14 row_mask:0xf bank_mask:0xf bound_ctrl:1
	v_mov_b32_dpp v219, v11 row_shr:2 row_mask:0xf bank_mask:0xf bound_ctrl:1
	v_mov_b32_dpp v221, v31 row_shl:14 row_mask:0xf bank_mask:0xf bound_ctrl:1
	v_pk_fma_f32 v[128:129], v[104:105], v[154:155], v[132:133]
	v_pk_mul_f32 v[132:133], v[136:137], v[152:153]
	v_pk_add_f32 v[136:137], v[214:215], v[216:217]
	v_pk_mul_f32 v[128:129], v[128:129], v[132:133]
	v_pk_add_f32 v[132:133], v[218:219], v[220:221]
	v_pk_fma_f32 v[136:137], v[90:91], v[136:137], v[140:141]
	v_cvt_pk_bf16_f32 v128, v128, v129
	v_pk_fma_f32 v[132:133], v[86:87], v[132:133], v[136:137]
	v_mov_b32_dpp v222, v6 row_shr:1 row_mask:0xf bank_mask:0xf bound_ctrl:1
	v_mul_f32_e32 v136, 0xbfb8aa3b, v133
	v_mul_f32_e32 v129, 0xbfb8aa3b, v132
	v_exp_f32_e32 v136, v136
	v_exp_f32_e32 v129, v129
	v_mov_b32_dpp v224, v34 row_shl:15 row_mask:0xf bank_mask:0xf bound_ctrl:1
	v_mov_b32_dpp v223, v7 row_shr:1 row_mask:0xf bank_mask:0xf bound_ctrl:1
	v_add_f32_e32 v136, 1.0, v136
	v_add_f32_e32 v129, 1.0, v129
	v_rcp_f32_e32 v137, v136
	v_rcp_f32_e32 v136, v129
	v_mov_b32_dpp v225, v35 row_shl:15 row_mask:0xf bank_mask:0xf bound_ctrl:1
	v_mov_b32_dpp v226, v6 row_shr:2 row_mask:0xf bank_mask:0xf bound_ctrl:1
	v_mov_b32_dpp v228, v34 row_shl:14 row_mask:0xf bank_mask:0xf bound_ctrl:1
	v_mov_b32_dpp v227, v7 row_shr:2 row_mask:0xf bank_mask:0xf bound_ctrl:1
	v_mov_b32_dpp v229, v35 row_shl:14 row_mask:0xf bank_mask:0xf bound_ctrl:1
	v_pk_add_f32 v[140:141], v[222:223], v[224:225]
	v_pk_add_f32 v[138:139], v[226:227], v[228:229]
	v_pk_fma_f32 v[134:135], v[118:119], v[140:141], v[146:147]
	v_pk_mul_f32 v[132:133], v[132:133], v[136:137]
	v_pk_fma_f32 v[130:131], v[106:107], v[138:139], v[134:135]
	s_nop 0
	v_pk_mul_f32 v[130:131], v[130:131], v[132:133]
	s_nop 0
	v_cvt_pk_bf16_f32 v129, v130, v131
	v_lshl_add_u64 v[130:131], v[208:209], 0, v[210:211]
	global_store_dwordx2 v[130:131], v[128:129], off
	s_and_saveexec_b64 s[76:77], s[42:43]
	s_cbranch_execz .LBB0_684
	v_mov_b64_e32 v[128:129], s[8:9]
	s_movk_i32 s71, 0x5800
	v_mad_u64_u32 v[128:129], s[78:79], v170, s71, v[128:129]
	v_mad_i32_i24 v129, v171, s71, v129
	v_lshl_add_u64 v[128:129], v[160:161], 2, v[128:129]
	global_store_dwordx4 v[128:129], v[8:11], off offset:512
	global_store_dwordx4 v[128:129], v[4:7], off offset:528
